# phase-0 weight transposes rotated: next item's 8 global loads issued right after the current item's LDS writes (loads in flight almost continuously)
# speedup vs baseline: 1.0013x; 1.0013x over previous
; #define LAS __attribute__((address_space(3)))
; __device__ __forceinline__ unsigned cvt_pk_bf16(float lo, float hi) { unsigned r; asm volatile("v_cvt_pk_bf16_f32 %0, %1, %2" : "=v"(r) : "v"(lo), "v"(hi)); return r; }
; __device__ __forceinline__ void p0_transpose_item(const float* W, int N, bf16_t* WT, int ldt, int coff, LAS float* scr, int item, int lane) {
;     const int nblk = N / 32, kb = item / nblk, nb = item % nblk, k0 = 64 * kb, n0 = 32 * nb;
;     { f32x4 v[8];
; #pragma unroll
;       for (int i = 0; i < 8; ++i) v[i] = __builtin_nontemporal_load((const f32x4*)(W + (size_t)(k0 + 8 * i + (lane >> 3)) * N + n0 + 4 * (lane & 7)));
; #pragma unroll
;       for (int i = 0; i < 8; ++i) { LAS float* d = scr + (8 * i + (lane >> 3)) * 33 + 4 * (lane & 7); d[0] = v[i].x; d[1] = v[i].y; d[2] = v[i].z; d[3] = v[i].w; } }
;     asm volatile("s_waitcnt lgkmcnt(0)" ::: "memory");
;     const int c = lane & 7;
; #pragma unroll
;     for (int j = 0; j < 4; ++j) { const int n = (lane >> 3) + 8 * j; const LAS float* s = scr + (8 * c) * 33 + n;
;         u32x4 o; o.x = cvt_pk_bf16(s[0 * 33], s[1 * 33]); o.y = cvt_pk_bf16(s[2 * 33], s[3 * 33]); o.z = cvt_pk_bf16(s[4 * 33], s[5 * 33]); o.w = cvt_pk_bf16(s[6 * 33], s[7 * 33]);
;         *(u32x4*)(WT + (size_t)(n0 + n) * ldt + coff + k0 + 8 * c) = o; }
;     asm volatile("s_waitcnt lgkmcnt(0)" ::: "memory");
; }
.LBB0_9:
	s_mul_hi_i32 s10, s0, 0x78787879
	s_lshr_b32 s11, s10, 31
	s_ashr_i32 s10, s10, 7
	s_add_i32 s11, s10, s11
	s_lshl_b32 s10, s11, 6
	s_mulk_i32 s11, 0xde00
	s_add_i32 s12, s1, s11
	v_or_b32_e32 v26, s10, v1
	s_ashr_i32 s13, s12, 31
	v_or_b32_e32 v28, 8, v26
	v_or_b32_e32 v30, 16, v26
	v_or_b32_e32 v31, 24, v26
	v_or_b32_e32 v34, 32, v26
	v_or_b32_e32 v35, 40, v26
	v_or_b32_e32 v38, 48, v26
	v_or_b32_e32 v39, 56, v26
	v_lshl_add_u64 v[24:25], s[12:13], 2, v[6:7]
	v_mad_i64_i32 v[26:27], s[14:15], v26, s3, v[24:25]
	v_mad_i64_i32 v[28:29], s[14:15], v28, s3, v[24:25]
	v_mad_i64_i32 v[32:33], s[14:15], v30, s3, v[24:25]
	v_mad_i64_i32 v[36:37], s[14:15], v31, s3, v[24:25]
	v_mad_i64_i32 v[40:41], s[14:15], v34, s3, v[24:25]
	v_mad_i64_i32 v[44:45], s[14:15], v35, s3, v[24:25]
	v_mad_i64_i32 v[48:49], s[14:15], v38, s3, v[24:25]
	v_mad_i64_i32 v[52:53], s[14:15], v39, s3, v[24:25]
	global_load_dwordx4 v[24:27], v[26:27], off nt
	s_nop 0
	global_load_dwordx4 v[28:31], v[28:29], off nt
	s_nop 0
	global_load_dwordx4 v[32:35], v[32:33], off nt
	s_nop 0
	global_load_dwordx4 v[36:39], v[36:37], off nt
	s_nop 0
	global_load_dwordx4 v[40:43], v[40:41], off nt
	s_nop 0
	global_load_dwordx4 v[44:47], v[44:45], off nt
	s_nop 0
	global_load_dwordx4 v[48:51], v[48:49], off nt
	s_nop 0
	global_load_dwordx4 v[52:55], v[52:53], off nt
	v_add_u32_e32 v58, s12, v1
	s_ashr_i32 s11, s10, 31
	v_ashrrev_i32_e32 v59, 31, v58
	v_lshl_add_u64 v[56:57], s[10:11], 1, v[8:9]
	v_lshlrev_b64 v[64:65], 12, v[58:59]
	v_add_u32_e32 v60, 8, v58
	v_lshl_add_u64 v[64:65], v[56:57], 0, v[64:65]
	v_ashrrev_i32_e32 v61, 31, v60
	v_lshlrev_b64 v[60:61], 12, v[60:61]
	v_add_u32_e32 v62, 16, v58
	v_lshl_add_u64 v[60:61], v[56:57], 0, v[60:61]
	v_ashrrev_i32_e32 v63, 31, v62
	v_lshlrev_b64 v[62:63], 12, v[62:63]
	v_lshl_add_u64 v[62:63], v[56:57], 0, v[62:63]
	s_add_i32 s0, s0, s94
	s_add_i32 s1, s1, s2
	s_cmpk_gt_i32 s0, 0x21ff
	s_waitcnt vmcnt(7)
	ds_write2_b32 v17, v24, v25 offset1:1
	ds_write2_b32 v17, v26, v27 offset0:2 offset1:3
	s_waitcnt vmcnt(6)
	ds_write2_b32 v3, v28, v29 offset1:1
	ds_write2_b32 v5, v30, v31 offset1:1
	s_waitcnt vmcnt(5)
	ds_write2_b32 v10, v32, v33 offset1:1
	ds_write2_b32 v11, v34, v35 offset1:1
	s_waitcnt vmcnt(4)
	ds_write2_b32 v12, v36, v37 offset1:1
	ds_write2_b32 v13, v38, v39 offset1:1
	s_waitcnt vmcnt(3)
	ds_write2_b32 v14, v40, v41 offset1:1
	ds_write2_b32 v15, v42, v43 offset1:1
	s_waitcnt vmcnt(2)
	ds_write2_b32 v18, v44, v45 offset1:1
	ds_write2_b32 v19, v46, v47 offset1:1
	s_waitcnt vmcnt(1)
	ds_write2_b32 v20, v48, v49 offset1:1
	ds_write2_b32 v21, v50, v51 offset1:1
	s_waitcnt vmcnt(0)
	ds_write2_b32 v22, v52, v53 offset1:1
	ds_write2_b32 v23, v54, v55 offset1:1
	s_branch .Lrot9_mid
.Lrot9_top:
	v_add_u32_e32 v58, s12, v1
	s_ashr_i32 s11, s10, 31
	v_ashrrev_i32_e32 v59, 31, v58
	v_lshl_add_u64 v[56:57], s[10:11], 1, v[8:9]
	v_lshlrev_b64 v[64:65], 12, v[58:59]
	v_add_u32_e32 v60, 8, v58
	v_lshl_add_u64 v[64:65], v[56:57], 0, v[64:65]
	v_ashrrev_i32_e32 v61, 31, v60
	v_lshlrev_b64 v[60:61], 12, v[60:61]
	v_add_u32_e32 v62, 16, v58
	v_lshl_add_u64 v[60:61], v[56:57], 0, v[60:61]
	v_ashrrev_i32_e32 v63, 31, v62
	v_lshlrev_b64 v[62:63], 12, v[62:63]
	v_lshl_add_u64 v[62:63], v[56:57], 0, v[62:63]
	s_add_i32 s0, s0, s94
	s_add_i32 s1, s1, s2
	s_cmpk_gt_i32 s0, 0x21ff
	s_waitcnt vmcnt(11)
	ds_write2_b32 v17, v24, v25 offset1:1
	ds_write2_b32 v17, v26, v27 offset0:2 offset1:3
	s_waitcnt vmcnt(10)
	ds_write2_b32 v3, v28, v29 offset1:1
	ds_write2_b32 v5, v30, v31 offset1:1
	s_waitcnt vmcnt(9)
	ds_write2_b32 v10, v32, v33 offset1:1
	ds_write2_b32 v11, v34, v35 offset1:1
	s_waitcnt vmcnt(8)
	ds_write2_b32 v12, v36, v37 offset1:1
	ds_write2_b32 v13, v38, v39 offset1:1
	s_waitcnt vmcnt(7)
	ds_write2_b32 v14, v40, v41 offset1:1
	ds_write2_b32 v15, v42, v43 offset1:1
	s_waitcnt vmcnt(6)
	ds_write2_b32 v18, v44, v45 offset1:1
	ds_write2_b32 v19, v46, v47 offset1:1
	s_waitcnt vmcnt(5)
	ds_write2_b32 v20, v48, v49 offset1:1
	ds_write2_b32 v21, v50, v51 offset1:1
	s_waitcnt vmcnt(4)
	ds_write2_b32 v22, v52, v53 offset1:1
	ds_write2_b32 v23, v54, v55 offset1:1
; #define LAS __attribute__((address_space(3)))
; __device__ __forceinline__ unsigned cvt_pk_bf16(float lo, float hi) { unsigned r; asm volatile("v_cvt_pk_bf16_f32 %0, %1, %2" : "=v"(r) : "v"(lo), "v"(hi)); return r; }
; __device__ __forceinline__ void p0_transpose_item(const float* W, int N, bf16_t* WT, int ldt, int coff, LAS float* scr, int item, int lane) {
;     const int nblk = N / 32, kb = item / nblk, nb = item % nblk, k0 = 64 * kb, n0 = 32 * nb;
;     { f32x4 v[8];
; #pragma unroll
;       for (int i = 0; i < 8; ++i) v[i] = __builtin_nontemporal_load((const f32x4*)(W + (size_t)(k0 + 8 * i + (lane >> 3)) * N + n0 + 4 * (lane & 7)));
; #pragma unroll
;       for (int i = 0; i < 8; ++i) { LAS float* d = scr + (8 * i + (lane >> 3)) * 33 + 4 * (lane & 7); d[0] = v[i].x; d[1] = v[i].y; d[2] = v[i].z; d[3] = v[i].w; } }
;     asm volatile("s_waitcnt lgkmcnt(0)" ::: "memory");
;     const int c = lane & 7;
; #pragma unroll
;     for (int j = 0; j < 4; ++j) { const int n = (lane >> 3) + 8 * j; const LAS float* s = scr + (8 * c) * 33 + n;
;         u32x4 o; o.x = cvt_pk_bf16(s[0 * 33], s[1 * 33]); o.y = cvt_pk_bf16(s[2 * 33], s[3 * 33]); o.z = cvt_pk_bf16(s[4 * 33], s[5 * 33]); o.w = cvt_pk_bf16(s[6 * 33], s[7 * 33]);
;         *(u32x4*)(WT + (size_t)(n0 + n) * ldt + coff + k0 + 8 * c) = o; }
;     asm volatile("s_waitcnt lgkmcnt(0)" ::: "memory");
; }
.Lrot9_mid:
	s_waitcnt lgkmcnt(0)
	s_cbranch_scc1 .Lrot9_nonext
	s_mul_hi_i32 s10, s0, 0x78787879
	s_lshr_b32 s11, s10, 31
	s_ashr_i32 s10, s10, 7
	s_add_i32 s11, s10, s11
	s_lshl_b32 s10, s11, 6
	s_mulk_i32 s11, 0xde00
	s_add_i32 s12, s1, s11
	v_or_b32_e32 v26, s10, v1
	s_ashr_i32 s13, s12, 31
	v_or_b32_e32 v28, 8, v26
	v_or_b32_e32 v30, 16, v26
	v_or_b32_e32 v31, 24, v26
	v_or_b32_e32 v34, 32, v26
	v_or_b32_e32 v35, 40, v26
	v_or_b32_e32 v38, 48, v26
	v_or_b32_e32 v39, 56, v26
	v_lshl_add_u64 v[24:25], s[12:13], 2, v[6:7]
	v_mad_i64_i32 v[26:27], s[14:15], v26, s3, v[24:25]
	v_mad_i64_i32 v[28:29], s[14:15], v28, s3, v[24:25]
	v_mad_i64_i32 v[32:33], s[14:15], v30, s3, v[24:25]
	v_mad_i64_i32 v[36:37], s[14:15], v31, s3, v[24:25]
	v_mad_i64_i32 v[40:41], s[14:15], v34, s3, v[24:25]
	v_mad_i64_i32 v[44:45], s[14:15], v35, s3, v[24:25]
	v_mad_i64_i32 v[48:49], s[14:15], v38, s3, v[24:25]
	v_mad_i64_i32 v[52:53], s[14:15], v39, s3, v[24:25]
	global_load_dwordx4 v[24:27], v[26:27], off nt
	s_nop 0
	global_load_dwordx4 v[28:31], v[28:29], off nt
	s_nop 0
	global_load_dwordx4 v[32:35], v[32:33], off nt
	s_nop 0
	global_load_dwordx4 v[36:39], v[36:37], off nt
	s_nop 0
	global_load_dwordx4 v[40:43], v[40:41], off nt
	s_nop 0
	global_load_dwordx4 v[44:47], v[44:45], off nt
	s_nop 0
	global_load_dwordx4 v[48:51], v[48:49], off nt
	s_nop 0
	global_load_dwordx4 v[52:55], v[52:53], off nt
.Lrot9_nonext:
	ds_read2_b32 v[92:93], v16 offset1:33
	ds_read2_b32 v[94:95], v16 offset0:66 offset1:99
	ds_read2_b32 v[96:97], v16 offset0:132 offset1:165
	ds_read2_b32 v[98:99], v16 offset0:198 offset1:231
	ds_read2_b32 v[100:101], v16 offset0:8 offset1:41
	ds_read2_b32 v[102:103], v16 offset0:74 offset1:107
	ds_read2_b32 v[104:105], v16 offset0:140 offset1:173
	ds_read2_b32 v[106:107], v16 offset0:206 offset1:239
	ds_read2_b32 v[108:109], v16 offset0:16 offset1:49
	ds_read2_b32 v[110:111], v16 offset0:82 offset1:115
	ds_read2_b32 v[112:113], v16 offset0:148 offset1:181
	ds_read2_b32 v[114:115], v16 offset0:214 offset1:247
	ds_read2_b32 v[116:117], v16 offset0:24 offset1:57
	ds_read2_b32 v[118:119], v16 offset0:90 offset1:123
	ds_read2_b32 v[120:121], v16 offset0:156 offset1:189
	ds_read2_b32 v[122:123], v16 offset0:222 offset1:255
	s_waitcnt lgkmcnt(0)
	s_nop 0
	v_cvt_pk_bf16_f32 v124, v92, v93
	s_nop 0
	v_cvt_pk_bf16_f32 v125, v94, v95
	s_nop 0
	v_cvt_pk_bf16_f32 v126, v96, v97
	s_nop 0
	v_cvt_pk_bf16_f32 v127, v98, v99
	global_store_dwordx4 v[64:65], v[124:127], off
	v_add_u32_e32 v130, 24, v58
	v_ashrrev_i32_e32 v131, 31, v130
	s_nop 0
	v_cvt_pk_bf16_f32 v124, v100, v101
	s_nop 0
	v_cvt_pk_bf16_f32 v125, v102, v103
	s_nop 0
	v_cvt_pk_bf16_f32 v126, v104, v105
	s_nop 0
	v_cvt_pk_bf16_f32 v127, v106, v107
	global_store_dwordx4 v[60:61], v[124:127], off
	v_lshlrev_b64 v[130:131], 12, v[130:131]
	v_lshl_add_u64 v[130:131], v[56:57], 0, v[130:131]
	s_nop 0
	v_cvt_pk_bf16_f32 v124, v108, v109
	s_nop 0
	v_cvt_pk_bf16_f32 v125, v110, v111
	s_nop 0
	v_cvt_pk_bf16_f32 v126, v112, v113
	s_nop 0
	v_cvt_pk_bf16_f32 v127, v114, v115
	global_store_dwordx4 v[62:63], v[124:127], off
	s_nop 0
	s_nop 0
	v_cvt_pk_bf16_f32 v124, v116, v117
	s_nop 0
	v_cvt_pk_bf16_f32 v125, v118, v119
	s_nop 0
	v_cvt_pk_bf16_f32 v126, v120, v121
	s_nop 0
	v_cvt_pk_bf16_f32 v127, v122, v123
	global_store_dwordx4 v[130:131], v[124:127], off
	s_waitcnt lgkmcnt(0)
	s_cmpk_gt_i32 s0, 0x21ff
	s_cbranch_scc0 .Lrot9_top

; #define LAS __attribute__((address_space(3)))
; __device__ __forceinline__ unsigned cvt_pk_bf16(float lo, float hi) { unsigned r; asm volatile("v_cvt_pk_bf16_f32 %0, %1, %2" : "=v"(r) : "v"(lo), "v"(hi)); return r; }
; __device__ __forceinline__ void p0_transpose_item(const float* W, int N, bf16_t* WT, int ldt, int coff, LAS float* scr, int item, int lane) {
;     const int nblk = N / 32, kb = item / nblk, nb = item % nblk, k0 = 64 * kb, n0 = 32 * nb;
;     { f32x4 v[8];
; #pragma unroll
;       for (int i = 0; i < 8; ++i) v[i] = __builtin_nontemporal_load((const f32x4*)(W + (size_t)(k0 + 8 * i + (lane >> 3)) * N + n0 + 4 * (lane & 7)));
; #pragma unroll
;       for (int i = 0; i < 8; ++i) { LAS float* d = scr + (8 * i + (lane >> 3)) * 33 + 4 * (lane & 7); d[0] = v[i].x; d[1] = v[i].y; d[2] = v[i].z; d[3] = v[i].w; } }
;     asm volatile("s_waitcnt lgkmcnt(0)" ::: "memory");
;     const int c = lane & 7;
; #pragma unroll
;     for (int j = 0; j < 4; ++j) { const int n = (lane >> 3) + 8 * j; const LAS float* s = scr + (8 * c) * 33 + n;
;         u32x4 o; o.x = cvt_pk_bf16(s[0 * 33], s[1 * 33]); o.y = cvt_pk_bf16(s[2 * 33], s[3 * 33]); o.z = cvt_pk_bf16(s[4 * 33], s[5 * 33]); o.w = cvt_pk_bf16(s[6 * 33], s[7 * 33]);
;         *(u32x4*)(WT + (size_t)(n0 + n) * ldt + coff + k0 + 8 * c) = o; }
;     asm volatile("s_waitcnt lgkmcnt(0)" ::: "memory");
; }
.LBB0_12:
	s_mul_hi_i32 s11, s1, 0x2aaaaaab
	s_lshr_b32 s12, s11, 31
	s_ashr_i32 s11, s11, 5
	s_add_i32 s11, s11, s12
	s_lshl_b32 s12, s11, 6
	s_mulk_i32 s11, 0xe800
	s_add_i32 s14, s2, s11
	v_or_b32_e32 v26, s12, v1
	s_ashr_i32 s15, s14, 31
	v_or_b32_e32 v28, 8, v26
	v_or_b32_e32 v30, 16, v26
	v_or_b32_e32 v31, 24, v26
	v_or_b32_e32 v34, 32, v26
	v_or_b32_e32 v35, 40, v26
	v_or_b32_e32 v38, 48, v26
	v_or_b32_e32 v39, 56, v26
	v_lshl_add_u64 v[24:25], s[14:15], 2, v[6:7]
	v_mad_i64_i32 v[26:27], s[16:17], v26, s10, v[24:25]
	v_mad_i64_i32 v[28:29], s[16:17], v28, s10, v[24:25]
	v_mad_i64_i32 v[32:33], s[16:17], v30, s10, v[24:25]
	v_mad_i64_i32 v[36:37], s[16:17], v31, s10, v[24:25]
	v_mad_i64_i32 v[40:41], s[16:17], v34, s10, v[24:25]
	v_mad_i64_i32 v[44:45], s[16:17], v35, s10, v[24:25]
	v_mad_i64_i32 v[48:49], s[16:17], v38, s10, v[24:25]
	v_mad_i64_i32 v[52:53], s[16:17], v39, s10, v[24:25]
	global_load_dwordx4 v[24:27], v[26:27], off nt
	s_nop 0
	global_load_dwordx4 v[28:31], v[28:29], off nt
	s_nop 0
	global_load_dwordx4 v[32:35], v[32:33], off nt
	s_nop 0
	global_load_dwordx4 v[36:39], v[36:37], off nt
	s_nop 0
	global_load_dwordx4 v[40:43], v[40:41], off nt
	s_nop 0
	global_load_dwordx4 v[44:47], v[44:45], off nt
	s_nop 0
	global_load_dwordx4 v[48:51], v[48:49], off nt
	s_nop 0
	global_load_dwordx4 v[52:55], v[52:53], off nt
	v_add_u32_e32 v58, s14, v1
	s_ashr_i32 s13, s12, 31
	v_ashrrev_i32_e32 v59, 31, v58
	v_lshl_add_u64 v[56:57], s[12:13], 1, v[8:9]
	v_lshlrev_b64 v[64:65], 12, v[58:59]
	v_add_u32_e32 v60, 8, v58
	v_lshl_add_u64 v[64:65], v[56:57], 0, v[64:65]
	v_ashrrev_i32_e32 v61, 31, v60
	v_lshlrev_b64 v[60:61], 12, v[60:61]
	v_add_u32_e32 v62, 16, v58
	v_lshl_add_u64 v[60:61], v[56:57], 0, v[60:61]
	v_ashrrev_i32_e32 v63, 31, v62
	v_lshlrev_b64 v[62:63], 12, v[62:63]
	v_lshl_add_u64 v[62:63], v[56:57], 0, v[62:63]
	s_add_i32 s1, s1, s94
	s_add_i32 s2, s2, s3
	s_cmpk_gt_i32 s1, 0x17ff
	s_waitcnt vmcnt(7)
	ds_write2_b32 v17, v24, v25 offset1:1
	ds_write2_b32 v17, v26, v27 offset0:2 offset1:3
	s_waitcnt vmcnt(6)
	ds_write2_b32 v3, v28, v29 offset1:1
	ds_write2_b32 v5, v30, v31 offset1:1
	s_waitcnt vmcnt(5)
	ds_write2_b32 v10, v32, v33 offset1:1
	ds_write2_b32 v11, v34, v35 offset1:1
	s_waitcnt vmcnt(4)
	ds_write2_b32 v12, v36, v37 offset1:1
	ds_write2_b32 v13, v38, v39 offset1:1
	s_waitcnt vmcnt(3)
	ds_write2_b32 v14, v40, v41 offset1:1
	ds_write2_b32 v15, v42, v43 offset1:1
	s_waitcnt vmcnt(2)
	ds_write2_b32 v18, v44, v45 offset1:1
	ds_write2_b32 v19, v46, v47 offset1:1
	s_waitcnt vmcnt(1)
	ds_write2_b32 v20, v48, v49 offset1:1
	ds_write2_b32 v21, v50, v51 offset1:1
	s_waitcnt vmcnt(0)
	ds_write2_b32 v22, v52, v53 offset1:1
	ds_write2_b32 v23, v54, v55 offset1:1
	s_branch .Lrot12_mid
.Lrot12_top:
	v_add_u32_e32 v58, s14, v1
	s_ashr_i32 s13, s12, 31
	v_ashrrev_i32_e32 v59, 31, v58
	v_lshl_add_u64 v[56:57], s[12:13], 1, v[8:9]
	v_lshlrev_b64 v[64:65], 12, v[58:59]
	v_add_u32_e32 v60, 8, v58
	v_lshl_add_u64 v[64:65], v[56:57], 0, v[64:65]
	v_ashrrev_i32_e32 v61, 31, v60
	v_lshlrev_b64 v[60:61], 12, v[60:61]
	v_add_u32_e32 v62, 16, v58
	v_lshl_add_u64 v[60:61], v[56:57], 0, v[60:61]
	v_ashrrev_i32_e32 v63, 31, v62
	v_lshlrev_b64 v[62:63], 12, v[62:63]
	v_lshl_add_u64 v[62:63], v[56:57], 0, v[62:63]
	s_add_i32 s1, s1, s94
	s_add_i32 s2, s2, s3
	s_cmpk_gt_i32 s1, 0x17ff
	s_waitcnt vmcnt(11)
	ds_write2_b32 v17, v24, v25 offset1:1
	ds_write2_b32 v17, v26, v27 offset0:2 offset1:3
	s_waitcnt vmcnt(10)
	ds_write2_b32 v3, v28, v29 offset1:1
	ds_write2_b32 v5, v30, v31 offset1:1
	s_waitcnt vmcnt(9)
	ds_write2_b32 v10, v32, v33 offset1:1
	ds_write2_b32 v11, v34, v35 offset1:1
	s_waitcnt vmcnt(8)
	ds_write2_b32 v12, v36, v37 offset1:1
	ds_write2_b32 v13, v38, v39 offset1:1
	s_waitcnt vmcnt(7)
	ds_write2_b32 v14, v40, v41 offset1:1
	ds_write2_b32 v15, v42, v43 offset1:1
	s_waitcnt vmcnt(6)
	ds_write2_b32 v18, v44, v45 offset1:1
	ds_write2_b32 v19, v46, v47 offset1:1
	s_waitcnt vmcnt(5)
	ds_write2_b32 v20, v48, v49 offset1:1
	ds_write2_b32 v21, v50, v51 offset1:1
	s_waitcnt vmcnt(4)
	ds_write2_b32 v22, v52, v53 offset1:1
	ds_write2_b32 v23, v54, v55 offset1:1
; #define LAS __attribute__((address_space(3)))
; __device__ __forceinline__ unsigned cvt_pk_bf16(float lo, float hi) { unsigned r; asm volatile("v_cvt_pk_bf16_f32 %0, %1, %2" : "=v"(r) : "v"(lo), "v"(hi)); return r; }
; __device__ __forceinline__ void p0_transpose_item(const float* W, int N, bf16_t* WT, int ldt, int coff, LAS float* scr, int item, int lane) {
;     const int nblk = N / 32, kb = item / nblk, nb = item % nblk, k0 = 64 * kb, n0 = 32 * nb;
;     { f32x4 v[8];
; #pragma unroll
;       for (int i = 0; i < 8; ++i) v[i] = __builtin_nontemporal_load((const f32x4*)(W + (size_t)(k0 + 8 * i + (lane >> 3)) * N + n0 + 4 * (lane & 7)));
; #pragma unroll
;       for (int i = 0; i < 8; ++i) { LAS float* d = scr + (8 * i + (lane >> 3)) * 33 + 4 * (lane & 7); d[0] = v[i].x; d[1] = v[i].y; d[2] = v[i].z; d[3] = v[i].w; } }
;     asm volatile("s_waitcnt lgkmcnt(0)" ::: "memory");
;     const int c = lane & 7;
; #pragma unroll
;     for (int j = 0; j < 4; ++j) { const int n = (lane >> 3) + 8 * j; const LAS float* s = scr + (8 * c) * 33 + n;
;         u32x4 o; o.x = cvt_pk_bf16(s[0 * 33], s[1 * 33]); o.y = cvt_pk_bf16(s[2 * 33], s[3 * 33]); o.z = cvt_pk_bf16(s[4 * 33], s[5 * 33]); o.w = cvt_pk_bf16(s[6 * 33], s[7 * 33]);
;         *(u32x4*)(WT + (size_t)(n0 + n) * ldt + coff + k0 + 8 * c) = o; }
;     asm volatile("s_waitcnt lgkmcnt(0)" ::: "memory");
; }
.Lrot12_mid:
	s_waitcnt lgkmcnt(0)
	s_cbranch_scc1 .Lrot12_nonext
	s_mul_hi_i32 s11, s1, 0x2aaaaaab
	s_lshr_b32 s12, s11, 31
	s_ashr_i32 s11, s11, 5
	s_add_i32 s11, s11, s12
	s_lshl_b32 s12, s11, 6
	s_mulk_i32 s11, 0xe800
	s_add_i32 s14, s2, s11
	v_or_b32_e32 v26, s12, v1
	s_ashr_i32 s15, s14, 31
	v_or_b32_e32 v28, 8, v26
	v_or_b32_e32 v30, 16, v26
	v_or_b32_e32 v31, 24, v26
	v_or_b32_e32 v34, 32, v26
	v_or_b32_e32 v35, 40, v26
	v_or_b32_e32 v38, 48, v26
	v_or_b32_e32 v39, 56, v26
	v_lshl_add_u64 v[24:25], s[14:15], 2, v[6:7]
	v_mad_i64_i32 v[26:27], s[16:17], v26, s10, v[24:25]
	v_mad_i64_i32 v[28:29], s[16:17], v28, s10, v[24:25]
	v_mad_i64_i32 v[32:33], s[16:17], v30, s10, v[24:25]
	v_mad_i64_i32 v[36:37], s[16:17], v31, s10, v[24:25]
	v_mad_i64_i32 v[40:41], s[16:17], v34, s10, v[24:25]
	v_mad_i64_i32 v[44:45], s[16:17], v35, s10, v[24:25]
	v_mad_i64_i32 v[48:49], s[16:17], v38, s10, v[24:25]
	v_mad_i64_i32 v[52:53], s[16:17], v39, s10, v[24:25]
	global_load_dwordx4 v[24:27], v[26:27], off nt
	s_nop 0
	global_load_dwordx4 v[28:31], v[28:29], off nt
	s_nop 0
	global_load_dwordx4 v[32:35], v[32:33], off nt
	s_nop 0
	global_load_dwordx4 v[36:39], v[36:37], off nt
	s_nop 0
	global_load_dwordx4 v[40:43], v[40:41], off nt
	s_nop 0
	global_load_dwordx4 v[44:47], v[44:45], off nt
	s_nop 0
	global_load_dwordx4 v[48:51], v[48:49], off nt
	s_nop 0
	global_load_dwordx4 v[52:55], v[52:53], off nt
.Lrot12_nonext:
	ds_read2_b32 v[92:93], v16 offset1:33
	ds_read2_b32 v[94:95], v16 offset0:66 offset1:99
	ds_read2_b32 v[96:97], v16 offset0:132 offset1:165
	ds_read2_b32 v[98:99], v16 offset0:198 offset1:231
	ds_read2_b32 v[100:101], v16 offset0:8 offset1:41
	ds_read2_b32 v[102:103], v16 offset0:74 offset1:107
	ds_read2_b32 v[104:105], v16 offset0:140 offset1:173
	ds_read2_b32 v[106:107], v16 offset0:206 offset1:239
	ds_read2_b32 v[108:109], v16 offset0:16 offset1:49
	ds_read2_b32 v[110:111], v16 offset0:82 offset1:115
	ds_read2_b32 v[112:113], v16 offset0:148 offset1:181
	ds_read2_b32 v[114:115], v16 offset0:214 offset1:247
	ds_read2_b32 v[116:117], v16 offset0:24 offset1:57
	ds_read2_b32 v[118:119], v16 offset0:90 offset1:123
	ds_read2_b32 v[120:121], v16 offset0:156 offset1:189
	ds_read2_b32 v[122:123], v16 offset0:222 offset1:255
	s_waitcnt lgkmcnt(0)
	s_nop 0
	v_cvt_pk_bf16_f32 v124, v92, v93
	s_nop 0
	v_cvt_pk_bf16_f32 v125, v94, v95
	s_nop 0
	v_cvt_pk_bf16_f32 v126, v96, v97
	s_nop 0
	v_cvt_pk_bf16_f32 v127, v98, v99
	global_store_dwordx4 v[64:65], v[124:127], off
	v_add_u32_e32 v130, 24, v58
	v_ashrrev_i32_e32 v131, 31, v130
	s_nop 0
	v_cvt_pk_bf16_f32 v124, v100, v101
	s_nop 0
	v_cvt_pk_bf16_f32 v125, v102, v103
	s_nop 0
	v_cvt_pk_bf16_f32 v126, v104, v105
	s_nop 0
	v_cvt_pk_bf16_f32 v127, v106, v107
	global_store_dwordx4 v[60:61], v[124:127], off
	v_lshlrev_b64 v[130:131], 12, v[130:131]
	v_lshl_add_u64 v[130:131], v[56:57], 0, v[130:131]
	s_nop 0
	v_cvt_pk_bf16_f32 v124, v108, v109
	s_nop 0
	v_cvt_pk_bf16_f32 v125, v110, v111
	s_nop 0
	v_cvt_pk_bf16_f32 v126, v112, v113
	s_nop 0
	v_cvt_pk_bf16_f32 v127, v114, v115
	global_store_dwordx4 v[62:63], v[124:127], off
	s_nop 0
	s_nop 0
	v_cvt_pk_bf16_f32 v124, v116, v117
	s_nop 0
	v_cvt_pk_bf16_f32 v125, v118, v119
	s_nop 0
	v_cvt_pk_bf16_f32 v126, v120, v121
	s_nop 0
	v_cvt_pk_bf16_f32 v127, v122, v123
	global_store_dwordx4 v[130:131], v[124:127], off
	s_waitcnt lgkmcnt(0)
	s_cmpk_gt_i32 s1, 0x17ff
	s_cbranch_scc0 .Lrot12_top

; #define LAS __attribute__((address_space(3)))
; __device__ __forceinline__ unsigned cvt_pk_bf16(float lo, float hi) { unsigned r; asm volatile("v_cvt_pk_bf16_f32 %0, %1, %2" : "=v"(r) : "v"(lo), "v"(hi)); return r; }
; __device__ __forceinline__ void p0_transpose_item(const float* W, int N, bf16_t* WT, int ldt, int coff, LAS float* scr, int item, int lane) {
;     const int nblk = N / 32, kb = item / nblk, nb = item % nblk, k0 = 64 * kb, n0 = 32 * nb;
;     { f32x4 v[8];
; #pragma unroll
;       for (int i = 0; i < 8; ++i) v[i] = __builtin_nontemporal_load((const f32x4*)(W + (size_t)(k0 + 8 * i + (lane >> 3)) * N + n0 + 4 * (lane & 7)));
; #pragma unroll
;       for (int i = 0; i < 8; ++i) { LAS float* d = scr + (8 * i + (lane >> 3)) * 33 + 4 * (lane & 7); d[0] = v[i].x; d[1] = v[i].y; d[2] = v[i].z; d[3] = v[i].w; } }
;     asm volatile("s_waitcnt lgkmcnt(0)" ::: "memory");
;     const int c = lane & 7;
; #pragma unroll
;     for (int j = 0; j < 4; ++j) { const int n = (lane >> 3) + 8 * j; const LAS float* s = scr + (8 * c) * 33 + n;
;         u32x4 o; o.x = cvt_pk_bf16(s[0 * 33], s[1 * 33]); o.y = cvt_pk_bf16(s[2 * 33], s[3 * 33]); o.z = cvt_pk_bf16(s[4 * 33], s[5 * 33]); o.w = cvt_pk_bf16(s[6 * 33], s[7 * 33]);
;         *(u32x4*)(WT + (size_t)(n0 + n) * ldt + coff + k0 + 8 * c) = o; }
;     asm volatile("s_waitcnt lgkmcnt(0)" ::: "memory");
; }
.LBB0_15:
	s_ashr_i32 s0, s11, 31
	s_lshr_b32 s0, s0, 26
	s_add_i32 s0, s11, s0
	s_and_b32 s2, s0, 0xffffffc0
	s_lshl_b32 s0, s0, 5
	s_and_b32 s0, s0, 0xfffff800
	v_or_b32_e32 v24, s2, v1
	s_sub_i32 s0, s12, s0
	v_or_b32_e32 v26, 8, v24
	v_or_b32_e32 v28, 16, v24
	v_or_b32_e32 v30, 24, v24
	v_or_b32_e32 v32, 32, v24
	v_or_b32_e32 v34, 40, v24
	v_or_b32_e32 v36, 48, v24
	v_or_b32_e32 v38, 56, v24
	v_ashrrev_i32_e32 v25, 31, v24
	s_ashr_i32 s1, s0, 31
	v_ashrrev_i32_e32 v27, 31, v26
	v_ashrrev_i32_e32 v29, 31, v28
	v_ashrrev_i32_e32 v31, 31, v30
	v_ashrrev_i32_e32 v33, 31, v32
	v_ashrrev_i32_e32 v35, 31, v34
	v_ashrrev_i32_e32 v37, 31, v36
	v_ashrrev_i32_e32 v39, 31, v38
	v_lshlrev_b64 v[24:25], 13, v[24:25]
	v_lshl_add_u64 v[40:41], s[0:1], 2, v[6:7]
	v_lshlrev_b64 v[26:27], 13, v[26:27]
	v_lshlrev_b64 v[28:29], 13, v[28:29]
	v_lshlrev_b64 v[30:31], 13, v[30:31]
	v_lshlrev_b64 v[32:33], 13, v[32:33]
	v_lshlrev_b64 v[34:35], 13, v[34:35]
	v_lshlrev_b64 v[36:37], 13, v[36:37]
	v_lshlrev_b64 v[38:39], 13, v[38:39]
	v_lshl_add_u64 v[24:25], v[40:41], 0, v[24:25]
	v_lshl_add_u64 v[42:43], v[40:41], 0, v[26:27]
	v_lshl_add_u64 v[44:45], v[40:41], 0, v[28:29]
	v_lshl_add_u64 v[46:47], v[40:41], 0, v[30:31]
	v_lshl_add_u64 v[48:49], v[40:41], 0, v[32:33]
	v_lshl_add_u64 v[50:51], v[40:41], 0, v[34:35]
	v_lshl_add_u64 v[52:53], v[40:41], 0, v[36:37]
	v_lshl_add_u64 v[54:55], v[40:41], 0, v[38:39]
	global_load_dwordx4 v[24:27], v[24:25], off nt
	s_nop 0
	global_load_dwordx4 v[28:31], v[42:43], off nt
	global_load_dwordx4 v[32:35], v[44:45], off nt
	global_load_dwordx4 v[36:39], v[46:47], off nt
	s_nop 0
	global_load_dwordx4 v[40:43], v[48:49], off nt
	global_load_dwordx4 v[44:47], v[50:51], off nt
	s_nop 0
	global_load_dwordx4 v[48:51], v[52:53], off nt
	s_nop 0
	global_load_dwordx4 v[52:55], v[54:55], off nt
	v_add_u32_e32 v58, s0, v1
	s_ashr_i32 s3, s2, 31
	v_ashrrev_i32_e32 v59, 31, v58
	v_lshl_add_u64 v[56:57], s[2:3], 1, v[8:9]
	v_lshlrev_b64 v[64:65], 12, v[58:59]
	v_add_u32_e32 v60, 8, v58
	v_lshl_add_u64 v[64:65], v[56:57], 0, v[64:65]
	v_ashrrev_i32_e32 v61, 31, v60
	v_lshlrev_b64 v[60:61], 12, v[60:61]
	v_add_u32_e32 v62, 16, v58
	v_lshl_add_u64 v[60:61], v[56:57], 0, v[60:61]
	v_ashrrev_i32_e32 v63, 31, v62
	v_lshlrev_b64 v[62:63], 12, v[62:63]
	v_lshl_add_u64 v[62:63], v[56:57], 0, v[62:63]
	s_add_i32 s11, s11, s94
	s_add_i32 s12, s12, s13
	s_cmpk_gt_i32 s11, 0x7ff
	s_waitcnt vmcnt(7)
	ds_write2_b32 v17, v24, v25 offset1:1
	ds_write2_b32 v17, v26, v27 offset0:2 offset1:3
	s_waitcnt vmcnt(6)
	ds_write2_b32 v3, v28, v29 offset1:1
	ds_write2_b32 v5, v30, v31 offset1:1
	s_waitcnt vmcnt(5)
	ds_write2_b32 v10, v32, v33 offset1:1
	ds_write2_b32 v11, v34, v35 offset1:1
	s_waitcnt vmcnt(4)
	ds_write2_b32 v12, v36, v37 offset1:1
	ds_write2_b32 v13, v38, v39 offset1:1
	s_waitcnt vmcnt(3)
	ds_write2_b32 v14, v40, v41 offset1:1
	ds_write2_b32 v15, v42, v43 offset1:1
	s_waitcnt vmcnt(2)
	ds_write2_b32 v18, v44, v45 offset1:1
	ds_write2_b32 v19, v46, v47 offset1:1
	s_waitcnt vmcnt(1)
	ds_write2_b32 v20, v48, v49 offset1:1
	ds_write2_b32 v21, v50, v51 offset1:1
	s_waitcnt vmcnt(0)
	ds_write2_b32 v22, v52, v53 offset1:1
	ds_write2_b32 v23, v54, v55 offset1:1
	s_branch .Lrot15_mid
.Lrot15_top:
	v_add_u32_e32 v58, s0, v1
	s_ashr_i32 s3, s2, 31
	v_ashrrev_i32_e32 v59, 31, v58
	v_lshl_add_u64 v[56:57], s[2:3], 1, v[8:9]
	v_lshlrev_b64 v[64:65], 12, v[58:59]
	v_add_u32_e32 v60, 8, v58
	v_lshl_add_u64 v[64:65], v[56:57], 0, v[64:65]
	v_ashrrev_i32_e32 v61, 31, v60
	v_lshlrev_b64 v[60:61], 12, v[60:61]
	v_add_u32_e32 v62, 16, v58
	v_lshl_add_u64 v[60:61], v[56:57], 0, v[60:61]
	v_ashrrev_i32_e32 v63, 31, v62
	v_lshlrev_b64 v[62:63], 12, v[62:63]
	v_lshl_add_u64 v[62:63], v[56:57], 0, v[62:63]
	s_add_i32 s11, s11, s94
	s_add_i32 s12, s12, s13
	s_cmpk_gt_i32 s11, 0x7ff
	s_waitcnt vmcnt(11)
	ds_write2_b32 v17, v24, v25 offset1:1
	ds_write2_b32 v17, v26, v27 offset0:2 offset1:3
	s_waitcnt vmcnt(10)
	ds_write2_b32 v3, v28, v29 offset1:1
	ds_write2_b32 v5, v30, v31 offset1:1
	s_waitcnt vmcnt(9)
	ds_write2_b32 v10, v32, v33 offset1:1
	ds_write2_b32 v11, v34, v35 offset1:1
	s_waitcnt vmcnt(8)
	ds_write2_b32 v12, v36, v37 offset1:1
	ds_write2_b32 v13, v38, v39 offset1:1
	s_waitcnt vmcnt(7)
	ds_write2_b32 v14, v40, v41 offset1:1
	ds_write2_b32 v15, v42, v43 offset1:1
	s_waitcnt vmcnt(6)
	ds_write2_b32 v18, v44, v45 offset1:1
	ds_write2_b32 v19, v46, v47 offset1:1
	s_waitcnt vmcnt(5)
	ds_write2_b32 v20, v48, v49 offset1:1
	ds_write2_b32 v21, v50, v51 offset1:1
	s_waitcnt vmcnt(4)
	ds_write2_b32 v22, v52, v53 offset1:1
	ds_write2_b32 v23, v54, v55 offset1:1
; #define LAS __attribute__((address_space(3)))
; __device__ __forceinline__ unsigned cvt_pk_bf16(float lo, float hi) { unsigned r; asm volatile("v_cvt_pk_bf16_f32 %0, %1, %2" : "=v"(r) : "v"(lo), "v"(hi)); return r; }
; __device__ __forceinline__ void p0_transpose_item(const float* W, int N, bf16_t* WT, int ldt, int coff, LAS float* scr, int item, int lane) {
;     const int nblk = N / 32, kb = item / nblk, nb = item % nblk, k0 = 64 * kb, n0 = 32 * nb;
;     { f32x4 v[8];
; #pragma unroll
;       for (int i = 0; i < 8; ++i) v[i] = __builtin_nontemporal_load((const f32x4*)(W + (size_t)(k0 + 8 * i + (lane >> 3)) * N + n0 + 4 * (lane & 7)));
; #pragma unroll
;       for (int i = 0; i < 8; ++i) { LAS float* d = scr + (8 * i + (lane >> 3)) * 33 + 4 * (lane & 7); d[0] = v[i].x; d[1] = v[i].y; d[2] = v[i].z; d[3] = v[i].w; } }
;     asm volatile("s_waitcnt lgkmcnt(0)" ::: "memory");
;     const int c = lane & 7;
; #pragma unroll
;     for (int j = 0; j < 4; ++j) { const int n = (lane >> 3) + 8 * j; const LAS float* s = scr + (8 * c) * 33 + n;
;         u32x4 o; o.x = cvt_pk_bf16(s[0 * 33], s[1 * 33]); o.y = cvt_pk_bf16(s[2 * 33], s[3 * 33]); o.z = cvt_pk_bf16(s[4 * 33], s[5 * 33]); o.w = cvt_pk_bf16(s[6 * 33], s[7 * 33]);
;         *(u32x4*)(WT + (size_t)(n0 + n) * ldt + coff + k0 + 8 * c) = o; }
;     asm volatile("s_waitcnt lgkmcnt(0)" ::: "memory");
; }
.Lrot15_mid:
	s_waitcnt lgkmcnt(0)
	s_cbranch_scc1 .Lrot15_nonext
	s_ashr_i32 s0, s11, 31
	s_lshr_b32 s0, s0, 26
	s_add_i32 s0, s11, s0
	s_and_b32 s2, s0, 0xffffffc0
	s_lshl_b32 s0, s0, 5
	s_and_b32 s0, s0, 0xfffff800
	v_or_b32_e32 v24, s2, v1
	s_sub_i32 s0, s12, s0
	v_or_b32_e32 v26, 8, v24
	v_or_b32_e32 v28, 16, v24
	v_or_b32_e32 v30, 24, v24
	v_or_b32_e32 v32, 32, v24
	v_or_b32_e32 v34, 40, v24
	v_or_b32_e32 v36, 48, v24
	v_or_b32_e32 v38, 56, v24
	v_ashrrev_i32_e32 v25, 31, v24
	s_ashr_i32 s1, s0, 31
	v_ashrrev_i32_e32 v27, 31, v26
	v_ashrrev_i32_e32 v29, 31, v28
	v_ashrrev_i32_e32 v31, 31, v30
	v_ashrrev_i32_e32 v33, 31, v32
	v_ashrrev_i32_e32 v35, 31, v34
	v_ashrrev_i32_e32 v37, 31, v36
	v_ashrrev_i32_e32 v39, 31, v38
	v_lshlrev_b64 v[24:25], 13, v[24:25]
	v_lshl_add_u64 v[40:41], s[0:1], 2, v[6:7]
	v_lshlrev_b64 v[26:27], 13, v[26:27]
	v_lshlrev_b64 v[28:29], 13, v[28:29]
	v_lshlrev_b64 v[30:31], 13, v[30:31]
	v_lshlrev_b64 v[32:33], 13, v[32:33]
	v_lshlrev_b64 v[34:35], 13, v[34:35]
	v_lshlrev_b64 v[36:37], 13, v[36:37]
	v_lshlrev_b64 v[38:39], 13, v[38:39]
	v_lshl_add_u64 v[24:25], v[40:41], 0, v[24:25]
	v_lshl_add_u64 v[42:43], v[40:41], 0, v[26:27]
	v_lshl_add_u64 v[44:45], v[40:41], 0, v[28:29]
	v_lshl_add_u64 v[46:47], v[40:41], 0, v[30:31]
	v_lshl_add_u64 v[48:49], v[40:41], 0, v[32:33]
	v_lshl_add_u64 v[50:51], v[40:41], 0, v[34:35]
	v_lshl_add_u64 v[52:53], v[40:41], 0, v[36:37]
	v_lshl_add_u64 v[54:55], v[40:41], 0, v[38:39]
	global_load_dwordx4 v[24:27], v[24:25], off nt
	s_nop 0
	global_load_dwordx4 v[28:31], v[42:43], off nt
	global_load_dwordx4 v[32:35], v[44:45], off nt
	global_load_dwordx4 v[36:39], v[46:47], off nt
	s_nop 0
	global_load_dwordx4 v[40:43], v[48:49], off nt
	global_load_dwordx4 v[44:47], v[50:51], off nt
	s_nop 0
	global_load_dwordx4 v[48:51], v[52:53], off nt
	s_nop 0
	global_load_dwordx4 v[52:55], v[54:55], off nt
.Lrot15_nonext:
	ds_read2_b32 v[92:93], v16 offset1:33
	ds_read2_b32 v[94:95], v16 offset0:66 offset1:99
	ds_read2_b32 v[96:97], v16 offset0:132 offset1:165
	ds_read2_b32 v[98:99], v16 offset0:198 offset1:231
	ds_read2_b32 v[100:101], v16 offset0:8 offset1:41
	ds_read2_b32 v[102:103], v16 offset0:74 offset1:107
	ds_read2_b32 v[104:105], v16 offset0:140 offset1:173
	ds_read2_b32 v[106:107], v16 offset0:206 offset1:239
	ds_read2_b32 v[108:109], v16 offset0:16 offset1:49
	ds_read2_b32 v[110:111], v16 offset0:82 offset1:115
	ds_read2_b32 v[112:113], v16 offset0:148 offset1:181
	ds_read2_b32 v[114:115], v16 offset0:214 offset1:247
	ds_read2_b32 v[116:117], v16 offset0:24 offset1:57
	ds_read2_b32 v[118:119], v16 offset0:90 offset1:123
	ds_read2_b32 v[120:121], v16 offset0:156 offset1:189
	ds_read2_b32 v[122:123], v16 offset0:222 offset1:255
	s_waitcnt lgkmcnt(0)
	s_nop 0
	v_cvt_pk_bf16_f32 v124, v92, v93
	s_nop 0
	v_cvt_pk_bf16_f32 v125, v94, v95
	s_nop 0
	v_cvt_pk_bf16_f32 v126, v96, v97
	s_nop 0
	v_cvt_pk_bf16_f32 v127, v98, v99
	global_store_dwordx4 v[64:65], v[124:127], off
	v_add_u32_e32 v130, 24, v58
	v_ashrrev_i32_e32 v131, 31, v130
	s_nop 0
	v_cvt_pk_bf16_f32 v124, v100, v101
	s_nop 0
	v_cvt_pk_bf16_f32 v125, v102, v103
	s_nop 0
	v_cvt_pk_bf16_f32 v126, v104, v105
	s_nop 0
	v_cvt_pk_bf16_f32 v127, v106, v107
	global_store_dwordx4 v[60:61], v[124:127], off
	v_lshlrev_b64 v[130:131], 12, v[130:131]
	v_lshl_add_u64 v[130:131], v[56:57], 0, v[130:131]
	s_nop 0
	v_cvt_pk_bf16_f32 v124, v108, v109
	s_nop 0
	v_cvt_pk_bf16_f32 v125, v110, v111
	s_nop 0
	v_cvt_pk_bf16_f32 v126, v112, v113
	s_nop 0
	v_cvt_pk_bf16_f32 v127, v114, v115
	global_store_dwordx4 v[62:63], v[124:127], off
	s_nop 0
	s_nop 0
	v_cvt_pk_bf16_f32 v124, v116, v117
	s_nop 0
	v_cvt_pk_bf16_f32 v125, v118, v119
	s_nop 0
	v_cvt_pk_bf16_f32 v126, v120, v121
	s_nop 0
	v_cvt_pk_bf16_f32 v127, v122, v123
	global_store_dwordx4 v[130:131], v[124:127], off
	s_waitcnt lgkmcnt(0)
	s_cmpk_gt_i32 s11, 0x7ff
	s_cbranch_scc0 .Lrot15_top

; #define LAS __attribute__((address_space(3)))
; __device__ __forceinline__ unsigned cvt_pk_bf16(float lo, float hi) { unsigned r; asm volatile("v_cvt_pk_bf16_f32 %0, %1, %2" : "=v"(r) : "v"(lo), "v"(hi)); return r; }
; __device__ __forceinline__ void p0_transpose_item(const float* W, int N, bf16_t* WT, int ldt, int coff, LAS float* scr, int item, int lane) {
;     const int nblk = N / 32, kb = item / nblk, nb = item % nblk, k0 = 64 * kb, n0 = 32 * nb;
;     { f32x4 v[8];
; #pragma unroll
;       for (int i = 0; i < 8; ++i) v[i] = __builtin_nontemporal_load((const f32x4*)(W + (size_t)(k0 + 8 * i + (lane >> 3)) * N + n0 + 4 * (lane & 7)));
; #pragma unroll
;       for (int i = 0; i < 8; ++i) { LAS float* d = scr + (8 * i + (lane >> 3)) * 33 + 4 * (lane & 7); d[0] = v[i].x; d[1] = v[i].y; d[2] = v[i].z; d[3] = v[i].w; } }
;     asm volatile("s_waitcnt lgkmcnt(0)" ::: "memory");
;     const int c = lane & 7;
; #pragma unroll
;     for (int j = 0; j < 4; ++j) { const int n = (lane >> 3) + 8 * j; const LAS float* s = scr + (8 * c) * 33 + n;
;         u32x4 o; o.x = cvt_pk_bf16(s[0 * 33], s[1 * 33]); o.y = cvt_pk_bf16(s[2 * 33], s[3 * 33]); o.z = cvt_pk_bf16(s[4 * 33], s[5 * 33]); o.w = cvt_pk_bf16(s[6 * 33], s[7 * 33]);
;         *(u32x4*)(WT + (size_t)(n0 + n) * ldt + coff + k0 + 8 * c) = o; }
;     asm volatile("s_waitcnt lgkmcnt(0)" ::: "memory");
; }
.LBB0_18:
	s_ashr_i32 s0, s10, 31
	s_lshr_b32 s0, s0, 26
	s_add_i32 s0, s10, s0
	s_ashr_i32 s13, s0, 6
	s_andn2_b32 s0, s0, 63
	s_lshl_b32 s1, s13, 11
	v_or_b32_e32 v26, s0, v1
	s_sub_i32 s14, s11, s1
	v_or_b32_e32 v28, 8, v26
	v_or_b32_e32 v30, 16, v26
	v_or_b32_e32 v32, 24, v26
	v_or_b32_e32 v34, 32, v26
	v_or_b32_e32 v36, 40, v26
	v_or_b32_e32 v38, 48, v26
	v_or_b32_e32 v40, 56, v26
	v_ashrrev_i32_e32 v27, 31, v26
	s_ashr_i32 s15, s14, 31
	v_ashrrev_i32_e32 v29, 31, v28
	v_ashrrev_i32_e32 v31, 31, v30
	v_ashrrev_i32_e32 v33, 31, v32
	v_ashrrev_i32_e32 v35, 31, v34
	v_ashrrev_i32_e32 v37, 31, v36
	v_ashrrev_i32_e32 v39, 31, v38
	v_ashrrev_i32_e32 v41, 31, v40
	v_lshlrev_b64 v[26:27], 13, v[26:27]
	v_lshl_add_u64 v[42:43], s[14:15], 2, v[6:7]
	v_lshlrev_b64 v[28:29], 13, v[28:29]
	v_lshlrev_b64 v[30:31], 13, v[30:31]
	v_lshlrev_b64 v[32:33], 13, v[32:33]
	v_lshlrev_b64 v[34:35], 13, v[34:35]
	v_lshlrev_b64 v[36:37], 13, v[36:37]
	v_lshlrev_b64 v[38:39], 13, v[38:39]
	v_lshlrev_b64 v[40:41], 13, v[40:41]
	v_lshl_add_u64 v[26:27], v[42:43], 0, v[26:27]
	v_lshl_add_u64 v[44:45], v[42:43], 0, v[28:29]
	v_lshl_add_u64 v[46:47], v[42:43], 0, v[30:31]
	v_lshl_add_u64 v[48:49], v[42:43], 0, v[32:33]
	v_lshl_add_u64 v[50:51], v[42:43], 0, v[34:35]
	v_lshl_add_u64 v[52:53], v[42:43], 0, v[36:37]
	v_lshl_add_u64 v[54:55], v[42:43], 0, v[38:39]
	v_lshl_add_u64 v[56:57], v[42:43], 0, v[40:41]
	global_load_dwordx4 v[26:29], v[26:27], off nt
	s_nop 0
	global_load_dwordx4 v[30:33], v[44:45], off nt
	global_load_dwordx4 v[34:37], v[46:47], off nt
	global_load_dwordx4 v[38:41], v[48:49], off nt
	s_nop 0
	global_load_dwordx4 v[42:45], v[50:51], off nt
	global_load_dwordx4 v[46:49], v[52:53], off nt
	s_nop 0
	global_load_dwordx4 v[50:53], v[54:55], off nt
	s_nop 0
	global_load_dwordx4 v[54:57], v[56:57], off nt
	s_mul_i32 s13, s13, 0xff400000
	s_ashr_i32 s1, s0, 31
	v_add_u32_e32 v60, s13, v3
	v_lshl_add_u64 v[58:59], s[0:1], 1, v[8:9]
	v_ashrrev_i32_e32 v61, 31, v60
	v_lshl_add_u64 v[66:67], v[58:59], 0, v[60:61]
	v_add_u32_e32 v62, 0xc000, v60
	v_ashrrev_i32_e32 v63, 31, v62
	v_lshl_add_u64 v[62:63], v[58:59], 0, v[62:63]
	v_add_u32_e32 v64, 0x18000, v60
	v_ashrrev_i32_e32 v65, 31, v64
	v_lshl_add_u64 v[64:65], v[58:59], 0, v[64:65]
	s_add_i32 s10, s10, s94
	s_add_i32 s11, s11, s12
	s_cmpk_gt_i32 s10, 0x1ff
	v_add_u32_e32 v3, s2, v3
	s_waitcnt vmcnt(7)
	ds_write2_b32 v17, v26, v27 offset1:1
	ds_write2_b32 v17, v28, v29 offset0:2 offset1:3
	s_waitcnt vmcnt(6)
	ds_write2_b32 v5, v30, v31 offset1:1
	ds_write2_b32 v10, v32, v33 offset1:1
	s_waitcnt vmcnt(5)
	ds_write2_b32 v11, v34, v35 offset1:1
	ds_write2_b32 v12, v36, v37 offset1:1
	s_waitcnt vmcnt(4)
	ds_write2_b32 v13, v38, v39 offset1:1
	ds_write2_b32 v14, v40, v41 offset1:1
	s_waitcnt vmcnt(3)
	ds_write2_b32 v15, v42, v43 offset1:1
	ds_write2_b32 v18, v44, v45 offset1:1
	s_waitcnt vmcnt(2)
	ds_write2_b32 v19, v46, v47 offset1:1
	ds_write2_b32 v20, v48, v49 offset1:1
	s_waitcnt vmcnt(1)
	ds_write2_b32 v21, v50, v51 offset1:1
	ds_write2_b32 v22, v52, v53 offset1:1
	s_waitcnt vmcnt(0)
	ds_write2_b32 v23, v54, v55 offset1:1
	ds_write2_b32 v24, v56, v57 offset1:1
	s_branch .Lrot18_mid
.Lrot18_top:
	s_mul_i32 s13, s13, 0xff400000
	s_ashr_i32 s1, s0, 31
	v_add_u32_e32 v60, s13, v3
	v_lshl_add_u64 v[58:59], s[0:1], 1, v[8:9]
	v_ashrrev_i32_e32 v61, 31, v60
	v_lshl_add_u64 v[66:67], v[58:59], 0, v[60:61]
	v_add_u32_e32 v62, 0xc000, v60
	v_ashrrev_i32_e32 v63, 31, v62
	v_lshl_add_u64 v[62:63], v[58:59], 0, v[62:63]
	v_add_u32_e32 v64, 0x18000, v60
	v_ashrrev_i32_e32 v65, 31, v64
	v_lshl_add_u64 v[64:65], v[58:59], 0, v[64:65]
	s_add_i32 s10, s10, s94
	s_add_i32 s11, s11, s12
	s_cmpk_gt_i32 s10, 0x1ff
	v_add_u32_e32 v3, s2, v3
	s_waitcnt vmcnt(11)
	ds_write2_b32 v17, v26, v27 offset1:1
	ds_write2_b32 v17, v28, v29 offset0:2 offset1:3
	s_waitcnt vmcnt(10)
	ds_write2_b32 v5, v30, v31 offset1:1
	ds_write2_b32 v10, v32, v33 offset1:1
	s_waitcnt vmcnt(9)
	ds_write2_b32 v11, v34, v35 offset1:1
	ds_write2_b32 v12, v36, v37 offset1:1
	s_waitcnt vmcnt(8)
	ds_write2_b32 v13, v38, v39 offset1:1
	ds_write2_b32 v14, v40, v41 offset1:1
	s_waitcnt vmcnt(7)
	ds_write2_b32 v15, v42, v43 offset1:1
	ds_write2_b32 v18, v44, v45 offset1:1
	s_waitcnt vmcnt(6)
	ds_write2_b32 v19, v46, v47 offset1:1
	ds_write2_b32 v20, v48, v49 offset1:1
	s_waitcnt vmcnt(5)
	ds_write2_b32 v21, v50, v51 offset1:1
	ds_write2_b32 v22, v52, v53 offset1:1
	s_waitcnt vmcnt(4)
	ds_write2_b32 v23, v54, v55 offset1:1
	ds_write2_b32 v24, v56, v57 offset1:1
; #define LAS __attribute__((address_space(3)))
; __device__ __forceinline__ unsigned cvt_pk_bf16(float lo, float hi) { unsigned r; asm volatile("v_cvt_pk_bf16_f32 %0, %1, %2" : "=v"(r) : "v"(lo), "v"(hi)); return r; }
; __device__ __forceinline__ void p0_transpose_item(const float* W, int N, bf16_t* WT, int ldt, int coff, LAS float* scr, int item, int lane) {
;     const int nblk = N / 32, kb = item / nblk, nb = item % nblk, k0 = 64 * kb, n0 = 32 * nb;
;     { f32x4 v[8];
; #pragma unroll
;       for (int i = 0; i < 8; ++i) v[i] = __builtin_nontemporal_load((const f32x4*)(W + (size_t)(k0 + 8 * i + (lane >> 3)) * N + n0 + 4 * (lane & 7)));
; #pragma unroll
;       for (int i = 0; i < 8; ++i) { LAS float* d = scr + (8 * i + (lane >> 3)) * 33 + 4 * (lane & 7); d[0] = v[i].x; d[1] = v[i].y; d[2] = v[i].z; d[3] = v[i].w; } }
;     asm volatile("s_waitcnt lgkmcnt(0)" ::: "memory");
;     const int c = lane & 7;
; #pragma unroll
;     for (int j = 0; j < 4; ++j) { const int n = (lane >> 3) + 8 * j; const LAS float* s = scr + (8 * c) * 33 + n;
;         u32x4 o; o.x = cvt_pk_bf16(s[0 * 33], s[1 * 33]); o.y = cvt_pk_bf16(s[2 * 33], s[3 * 33]); o.z = cvt_pk_bf16(s[4 * 33], s[5 * 33]); o.w = cvt_pk_bf16(s[6 * 33], s[7 * 33]);
;         *(u32x4*)(WT + (size_t)(n0 + n) * ldt + coff + k0 + 8 * c) = o; }
;     asm volatile("s_waitcnt lgkmcnt(0)" ::: "memory");
; }
.Lrot18_mid:
	s_waitcnt lgkmcnt(0)
	s_cbranch_scc1 .Lrot18_nonext
	s_ashr_i32 s0, s10, 31
	s_lshr_b32 s0, s0, 26
	s_add_i32 s0, s10, s0
	s_ashr_i32 s13, s0, 6
	s_andn2_b32 s0, s0, 63
	s_lshl_b32 s1, s13, 11
	v_or_b32_e32 v26, s0, v1
	s_sub_i32 s14, s11, s1
	v_or_b32_e32 v28, 8, v26
	v_or_b32_e32 v30, 16, v26
	v_or_b32_e32 v32, 24, v26
	v_or_b32_e32 v34, 32, v26
	v_or_b32_e32 v36, 40, v26
	v_or_b32_e32 v38, 48, v26
	v_or_b32_e32 v40, 56, v26
	v_ashrrev_i32_e32 v27, 31, v26
	s_ashr_i32 s15, s14, 31
	v_ashrrev_i32_e32 v29, 31, v28
	v_ashrrev_i32_e32 v31, 31, v30
	v_ashrrev_i32_e32 v33, 31, v32
	v_ashrrev_i32_e32 v35, 31, v34
	v_ashrrev_i32_e32 v37, 31, v36
	v_ashrrev_i32_e32 v39, 31, v38
	v_ashrrev_i32_e32 v41, 31, v40
	v_lshlrev_b64 v[26:27], 13, v[26:27]
	v_lshl_add_u64 v[42:43], s[14:15], 2, v[6:7]
	v_lshlrev_b64 v[28:29], 13, v[28:29]
	v_lshlrev_b64 v[30:31], 13, v[30:31]
	v_lshlrev_b64 v[32:33], 13, v[32:33]
	v_lshlrev_b64 v[34:35], 13, v[34:35]
	v_lshlrev_b64 v[36:37], 13, v[36:37]
	v_lshlrev_b64 v[38:39], 13, v[38:39]
	v_lshlrev_b64 v[40:41], 13, v[40:41]
	v_lshl_add_u64 v[26:27], v[42:43], 0, v[26:27]
	v_lshl_add_u64 v[44:45], v[42:43], 0, v[28:29]
	v_lshl_add_u64 v[46:47], v[42:43], 0, v[30:31]
	v_lshl_add_u64 v[48:49], v[42:43], 0, v[32:33]
	v_lshl_add_u64 v[50:51], v[42:43], 0, v[34:35]
	v_lshl_add_u64 v[52:53], v[42:43], 0, v[36:37]
	v_lshl_add_u64 v[54:55], v[42:43], 0, v[38:39]
	v_lshl_add_u64 v[56:57], v[42:43], 0, v[40:41]
	global_load_dwordx4 v[26:29], v[26:27], off nt
	s_nop 0
	global_load_dwordx4 v[30:33], v[44:45], off nt
	global_load_dwordx4 v[34:37], v[46:47], off nt
	global_load_dwordx4 v[38:41], v[48:49], off nt
	s_nop 0
	global_load_dwordx4 v[42:45], v[50:51], off nt
	global_load_dwordx4 v[46:49], v[52:53], off nt
	s_nop 0
	global_load_dwordx4 v[50:53], v[54:55], off nt
	s_nop 0
	global_load_dwordx4 v[54:57], v[56:57], off nt
.Lrot18_nonext:
	ds_read2_b32 v[92:93], v16 offset1:33
	ds_read2_b32 v[94:95], v16 offset0:66 offset1:99
	ds_read2_b32 v[96:97], v16 offset0:132 offset1:165
	ds_read2_b32 v[98:99], v16 offset0:198 offset1:231
	ds_read2_b32 v[100:101], v16 offset0:8 offset1:41
	ds_read2_b32 v[102:103], v16 offset0:74 offset1:107
	ds_read2_b32 v[104:105], v16 offset0:140 offset1:173
	ds_read2_b32 v[106:107], v16 offset0:206 offset1:239
	ds_read2_b32 v[108:109], v16 offset0:16 offset1:49
	ds_read2_b32 v[110:111], v16 offset0:82 offset1:115
	ds_read2_b32 v[112:113], v16 offset0:148 offset1:181
	ds_read2_b32 v[114:115], v16 offset0:214 offset1:247
	ds_read2_b32 v[116:117], v16 offset0:24 offset1:57
	ds_read2_b32 v[118:119], v16 offset0:90 offset1:123
	ds_read2_b32 v[120:121], v16 offset0:156 offset1:189
	ds_read2_b32 v[122:123], v16 offset0:222 offset1:255
	s_waitcnt lgkmcnt(0)
	s_nop 0
	v_cvt_pk_bf16_f32 v126, v92, v93
	s_nop 0
	v_cvt_pk_bf16_f32 v127, v94, v95
	s_nop 0
	v_cvt_pk_bf16_f32 v128, v96, v97
	s_nop 0
	v_cvt_pk_bf16_f32 v129, v98, v99
	global_store_dwordx4 v[66:67], v[126:129], off
	v_add_u32_e32 v132, 0x24000, v60
	v_ashrrev_i32_e32 v133, 31, v132
	s_nop 0
	v_cvt_pk_bf16_f32 v126, v100, v101
	s_nop 0
	v_cvt_pk_bf16_f32 v127, v102, v103
	s_nop 0
	v_cvt_pk_bf16_f32 v128, v104, v105
	s_nop 0
	v_cvt_pk_bf16_f32 v129, v106, v107
	global_store_dwordx4 v[62:63], v[126:129], off
	v_lshl_add_u64 v[132:133], v[58:59], 0, v[132:133]
	s_nop 0
	v_cvt_pk_bf16_f32 v126, v108, v109
	s_nop 0
	v_cvt_pk_bf16_f32 v127, v110, v111
	s_nop 0
	v_cvt_pk_bf16_f32 v128, v112, v113
	s_nop 0
	v_cvt_pk_bf16_f32 v129, v114, v115
	global_store_dwordx4 v[64:65], v[126:129], off
	s_nop 0
	s_nop 0
	v_cvt_pk_bf16_f32 v126, v116, v117
	s_nop 0
	v_cvt_pk_bf16_f32 v127, v118, v119
	s_nop 0
	v_cvt_pk_bf16_f32 v128, v120, v121
	s_nop 0
	v_cvt_pk_bf16_f32 v129, v122, v123
	global_store_dwordx4 v[132:133], v[126:129], off
	s_waitcnt lgkmcnt(0)
	s_cmpk_gt_i32 s10, 0x1ff
	s_cbranch_scc0 .Lrot18_top

; #define LAS __attribute__((address_space(3)))
; __device__ __forceinline__ unsigned cvt_pk_bf16(float lo, float hi) { unsigned r; asm volatile("v_cvt_pk_bf16_f32 %0, %1, %2" : "=v"(r) : "v"(lo), "v"(hi)); return r; }
; __device__ __forceinline__ void p0_transpose_item(const float* W, int N, bf16_t* WT, int ldt, int coff, LAS float* scr, int item, int lane) {
;     const int nblk = N / 32, kb = item / nblk, nb = item % nblk, k0 = 64 * kb, n0 = 32 * nb;
;     { f32x4 v[8];
; #pragma unroll
;       for (int i = 0; i < 8; ++i) v[i] = __builtin_nontemporal_load((const f32x4*)(W + (size_t)(k0 + 8 * i + (lane >> 3)) * N + n0 + 4 * (lane & 7)));
; #pragma unroll
;       for (int i = 0; i < 8; ++i) { LAS float* d = scr + (8 * i + (lane >> 3)) * 33 + 4 * (lane & 7); d[0] = v[i].x; d[1] = v[i].y; d[2] = v[i].z; d[3] = v[i].w; } }
;     asm volatile("s_waitcnt lgkmcnt(0)" ::: "memory");
;     const int c = lane & 7;
; #pragma unroll
;     for (int j = 0; j < 4; ++j) { const int n = (lane >> 3) + 8 * j; const LAS float* s = scr + (8 * c) * 33 + n;
;         u32x4 o; o.x = cvt_pk_bf16(s[0 * 33], s[1 * 33]); o.y = cvt_pk_bf16(s[2 * 33], s[3 * 33]); o.z = cvt_pk_bf16(s[4 * 33], s[5 * 33]); o.w = cvt_pk_bf16(s[6 * 33], s[7 * 33]);
;         *(u32x4*)(WT + (size_t)(n0 + n) * ldt + coff + k0 + 8 * c) = o; }
;     asm volatile("s_waitcnt lgkmcnt(0)" ::: "memory");
; }
.LBB0_21:
	s_ashr_i32 s0, s10, 31
	s_lshr_b32 s0, s0, 26
	s_add_i32 s0, s10, s0
	s_ashr_i32 s13, s0, 6
	s_andn2_b32 s0, s0, 63
	s_lshl_b32 s1, s13, 11
	v_or_b32_e32 v26, s0, v1
	s_sub_i32 s14, s11, s1
	v_or_b32_e32 v28, 8, v26
	v_or_b32_e32 v30, 16, v26
	v_or_b32_e32 v32, 24, v26
	v_or_b32_e32 v34, 32, v26
	v_or_b32_e32 v36, 40, v26
	v_or_b32_e32 v38, 48, v26
	v_or_b32_e32 v40, 56, v26
	v_ashrrev_i32_e32 v27, 31, v26
	s_ashr_i32 s15, s14, 31
	v_ashrrev_i32_e32 v29, 31, v28
	v_ashrrev_i32_e32 v31, 31, v30
	v_ashrrev_i32_e32 v33, 31, v32
	v_ashrrev_i32_e32 v35, 31, v34
	v_ashrrev_i32_e32 v37, 31, v36
	v_ashrrev_i32_e32 v39, 31, v38
	v_ashrrev_i32_e32 v41, 31, v40
	v_lshlrev_b64 v[26:27], 13, v[26:27]
	v_lshl_add_u64 v[42:43], s[14:15], 2, v[6:7]
	v_lshlrev_b64 v[28:29], 13, v[28:29]
	v_lshlrev_b64 v[30:31], 13, v[30:31]
	v_lshlrev_b64 v[32:33], 13, v[32:33]
	v_lshlrev_b64 v[34:35], 13, v[34:35]
	v_lshlrev_b64 v[36:37], 13, v[36:37]
	v_lshlrev_b64 v[38:39], 13, v[38:39]
	v_lshlrev_b64 v[40:41], 13, v[40:41]
	v_lshl_add_u64 v[26:27], v[42:43], 0, v[26:27]
	v_lshl_add_u64 v[44:45], v[42:43], 0, v[28:29]
	v_lshl_add_u64 v[46:47], v[42:43], 0, v[30:31]
	v_lshl_add_u64 v[48:49], v[42:43], 0, v[32:33]
	v_lshl_add_u64 v[50:51], v[42:43], 0, v[34:35]
	v_lshl_add_u64 v[52:53], v[42:43], 0, v[36:37]
	v_lshl_add_u64 v[54:55], v[42:43], 0, v[38:39]
	v_lshl_add_u64 v[56:57], v[42:43], 0, v[40:41]
	global_load_dwordx4 v[26:29], v[26:27], off nt
	s_nop 0
	global_load_dwordx4 v[30:33], v[44:45], off nt
	global_load_dwordx4 v[34:37], v[46:47], off nt
	global_load_dwordx4 v[38:41], v[48:49], off nt
	s_nop 0
	global_load_dwordx4 v[42:45], v[50:51], off nt
	global_load_dwordx4 v[46:49], v[52:53], off nt
	s_nop 0
	global_load_dwordx4 v[50:53], v[54:55], off nt
	s_nop 0
	global_load_dwordx4 v[54:57], v[56:57], off nt
	s_mul_i32 s13, s13, 0xff400000
	s_ashr_i32 s1, s0, 31
	v_add_u32_e32 v60, s13, v3
	v_lshl_add_u64 v[58:59], s[0:1], 1, v[8:9]
	v_ashrrev_i32_e32 v61, 31, v60
	v_lshl_add_u64 v[66:67], v[58:59], 0, v[60:61]
	v_add_u32_e32 v62, 0xc000, v60
	v_ashrrev_i32_e32 v63, 31, v62
	v_lshl_add_u64 v[62:63], v[58:59], 0, v[62:63]
	v_add_u32_e32 v64, 0x18000, v60
	v_ashrrev_i32_e32 v65, 31, v64
	v_lshl_add_u64 v[64:65], v[58:59], 0, v[64:65]
	s_add_i32 s10, s10, s94
	s_add_i32 s11, s11, s12
	s_cmpk_gt_i32 s10, 0x5ff
	v_add_u32_e32 v3, s2, v3
	s_waitcnt vmcnt(7)
	ds_write2_b32 v17, v26, v27 offset1:1
	ds_write2_b32 v17, v28, v29 offset0:2 offset1:3
	s_waitcnt vmcnt(6)
	ds_write2_b32 v5, v30, v31 offset1:1
	ds_write2_b32 v10, v32, v33 offset1:1
	s_waitcnt vmcnt(5)
	ds_write2_b32 v11, v34, v35 offset1:1
	ds_write2_b32 v12, v36, v37 offset1:1
	s_waitcnt vmcnt(4)
	ds_write2_b32 v13, v38, v39 offset1:1
	ds_write2_b32 v14, v40, v41 offset1:1
	s_waitcnt vmcnt(3)
	ds_write2_b32 v15, v42, v43 offset1:1
	ds_write2_b32 v18, v44, v45 offset1:1
	s_waitcnt vmcnt(2)
	ds_write2_b32 v19, v46, v47 offset1:1
	ds_write2_b32 v20, v48, v49 offset1:1
	s_waitcnt vmcnt(1)
	ds_write2_b32 v21, v50, v51 offset1:1
	ds_write2_b32 v22, v52, v53 offset1:1
	s_waitcnt vmcnt(0)
	ds_write2_b32 v23, v54, v55 offset1:1
	ds_write2_b32 v24, v56, v57 offset1:1
	s_branch .Lrot21_mid
.Lrot21_top:
	s_mul_i32 s13, s13, 0xff400000
	s_ashr_i32 s1, s0, 31
	v_add_u32_e32 v60, s13, v3
	v_lshl_add_u64 v[58:59], s[0:1], 1, v[8:9]
	v_ashrrev_i32_e32 v61, 31, v60
	v_lshl_add_u64 v[66:67], v[58:59], 0, v[60:61]
	v_add_u32_e32 v62, 0xc000, v60
	v_ashrrev_i32_e32 v63, 31, v62
	v_lshl_add_u64 v[62:63], v[58:59], 0, v[62:63]
	v_add_u32_e32 v64, 0x18000, v60
	v_ashrrev_i32_e32 v65, 31, v64
	v_lshl_add_u64 v[64:65], v[58:59], 0, v[64:65]
	s_add_i32 s10, s10, s94
	s_add_i32 s11, s11, s12
	s_cmpk_gt_i32 s10, 0x5ff
	v_add_u32_e32 v3, s2, v3
	s_waitcnt vmcnt(11)
	ds_write2_b32 v17, v26, v27 offset1:1
	ds_write2_b32 v17, v28, v29 offset0:2 offset1:3
	s_waitcnt vmcnt(10)
	ds_write2_b32 v5, v30, v31 offset1:1
	ds_write2_b32 v10, v32, v33 offset1:1
	s_waitcnt vmcnt(9)
	ds_write2_b32 v11, v34, v35 offset1:1
	ds_write2_b32 v12, v36, v37 offset1:1
	s_waitcnt vmcnt(8)
	ds_write2_b32 v13, v38, v39 offset1:1
	ds_write2_b32 v14, v40, v41 offset1:1
	s_waitcnt vmcnt(7)
	ds_write2_b32 v15, v42, v43 offset1:1
	ds_write2_b32 v18, v44, v45 offset1:1
	s_waitcnt vmcnt(6)
	ds_write2_b32 v19, v46, v47 offset1:1
	ds_write2_b32 v20, v48, v49 offset1:1
	s_waitcnt vmcnt(5)
	ds_write2_b32 v21, v50, v51 offset1:1
	ds_write2_b32 v22, v52, v53 offset1:1
	s_waitcnt vmcnt(4)
	ds_write2_b32 v23, v54, v55 offset1:1
	ds_write2_b32 v24, v56, v57 offset1:1

; #define LAS __attribute__((address_space(3)))
; __device__ __forceinline__ unsigned cvt_pk_bf16(float lo, float hi) { unsigned r; asm volatile("v_cvt_pk_bf16_f32 %0, %1, %2" : "=v"(r) : "v"(lo), "v"(hi)); return r; }
; __device__ __forceinline__ void p0_transpose_item(const float* W, int N, bf16_t* WT, int ldt, int coff, LAS float* scr, int item, int lane) {
;     const int nblk = N / 32, kb = item / nblk, nb = item % nblk, k0 = 64 * kb, n0 = 32 * nb;
;     { f32x4 v[8];
; #pragma unroll
;       for (int i = 0; i < 8; ++i) v[i] = __builtin_nontemporal_load((const f32x4*)(W + (size_t)(k0 + 8 * i + (lane >> 3)) * N + n0 + 4 * (lane & 7)));
; #pragma unroll
;       for (int i = 0; i < 8; ++i) { LAS float* d = scr + (8 * i + (lane >> 3)) * 33 + 4 * (lane & 7); d[0] = v[i].x; d[1] = v[i].y; d[2] = v[i].z; d[3] = v[i].w; } }
;     asm volatile("s_waitcnt lgkmcnt(0)" ::: "memory");
;     const int c = lane & 7;
; #pragma unroll
;     for (int j = 0; j < 4; ++j) { const int n = (lane >> 3) + 8 * j; const LAS float* s = scr + (8 * c) * 33 + n;
;         u32x4 o; o.x = cvt_pk_bf16(s[0 * 33], s[1 * 33]); o.y = cvt_pk_bf16(s[2 * 33], s[3 * 33]); o.z = cvt_pk_bf16(s[4 * 33], s[5 * 33]); o.w = cvt_pk_bf16(s[6 * 33], s[7 * 33]);
;         *(u32x4*)(WT + (size_t)(n0 + n) * ldt + coff + k0 + 8 * c) = o; }
;     asm volatile("s_waitcnt lgkmcnt(0)" ::: "memory");
; }
.Lrot21_nonext:
	ds_read2_b32 v[92:93], v16 offset1:33
	ds_read2_b32 v[94:95], v16 offset0:66 offset1:99
	ds_read2_b32 v[96:97], v16 offset0:132 offset1:165
	ds_read2_b32 v[98:99], v16 offset0:198 offset1:231
	ds_read2_b32 v[100:101], v16 offset0:8 offset1:41
	ds_read2_b32 v[102:103], v16 offset0:74 offset1:107
	ds_read2_b32 v[104:105], v16 offset0:140 offset1:173
	ds_read2_b32 v[106:107], v16 offset0:206 offset1:239
	ds_read2_b32 v[108:109], v16 offset0:16 offset1:49
	ds_read2_b32 v[110:111], v16 offset0:82 offset1:115
	ds_read2_b32 v[112:113], v16 offset0:148 offset1:181
	ds_read2_b32 v[114:115], v16 offset0:214 offset1:247
	ds_read2_b32 v[116:117], v16 offset0:24 offset1:57
	ds_read2_b32 v[118:119], v16 offset0:90 offset1:123
	ds_read2_b32 v[120:121], v16 offset0:156 offset1:189
	ds_read2_b32 v[122:123], v16 offset0:222 offset1:255
	s_waitcnt lgkmcnt(0)
	s_nop 0
	v_cvt_pk_bf16_f32 v126, v92, v93
	s_nop 0
	v_cvt_pk_bf16_f32 v127, v94, v95
	s_nop 0
	v_cvt_pk_bf16_f32 v128, v96, v97
	s_nop 0
	v_cvt_pk_bf16_f32 v129, v98, v99
	global_store_dwordx4 v[66:67], v[126:129], off
	v_add_u32_e32 v132, 0x24000, v60
	v_ashrrev_i32_e32 v133, 31, v132
	s_nop 0
	v_cvt_pk_bf16_f32 v126, v100, v101
	s_nop 0
	v_cvt_pk_bf16_f32 v127, v102, v103
	s_nop 0
	v_cvt_pk_bf16_f32 v128, v104, v105
	s_nop 0
	v_cvt_pk_bf16_f32 v129, v106, v107
	global_store_dwordx4 v[62:63], v[126:129], off
	v_lshl_add_u64 v[132:133], v[58:59], 0, v[132:133]
	s_nop 0
	v_cvt_pk_bf16_f32 v126, v108, v109
	s_nop 0
	v_cvt_pk_bf16_f32 v127, v110, v111
	s_nop 0
	v_cvt_pk_bf16_f32 v128, v112, v113
	s_nop 0
	v_cvt_pk_bf16_f32 v129, v114, v115
	global_store_dwordx4 v[64:65], v[126:129], off
	s_nop 0
	s_nop 0
	v_cvt_pk_bf16_f32 v126, v116, v117
	s_nop 0
	v_cvt_pk_bf16_f32 v127, v118, v119
	s_nop 0
	v_cvt_pk_bf16_f32 v128, v120, v121
	s_nop 0
	v_cvt_pk_bf16_f32 v129, v122, v123
	global_store_dwordx4 v[132:133], v[126:129], off
	s_waitcnt lgkmcnt(0)
	s_cmpk_gt_i32 s10, 0x5ff
	s_cbranch_scc0 .Lrot21_top

; #define LAS __attribute__((address_space(3)))
; __device__ __forceinline__ unsigned cvt_pk_bf16(float lo, float hi) { unsigned r; asm volatile("v_cvt_pk_bf16_f32 %0, %1, %2" : "=v"(r) : "v"(lo), "v"(hi)); return r; }
; __device__ __forceinline__ void p0_transpose_item(const float* W, int N, bf16_t* WT, int ldt, int coff, LAS float* scr, int item, int lane) {
;     const int nblk = N / 32, kb = item / nblk, nb = item % nblk, k0 = 64 * kb, n0 = 32 * nb;
;     { f32x4 v[8];
; #pragma unroll
;       for (int i = 0; i < 8; ++i) v[i] = __builtin_nontemporal_load((const f32x4*)(W + (size_t)(k0 + 8 * i + (lane >> 3)) * N + n0 + 4 * (lane & 7)));
; #pragma unroll
;       for (int i = 0; i < 8; ++i) { LAS float* d = scr + (8 * i + (lane >> 3)) * 33 + 4 * (lane & 7); d[0] = v[i].x; d[1] = v[i].y; d[2] = v[i].z; d[3] = v[i].w; } }
;     asm volatile("s_waitcnt lgkmcnt(0)" ::: "memory");
;     const int c = lane & 7;
; #pragma unroll
;     for (int j = 0; j < 4; ++j) { const int n = (lane >> 3) + 8 * j; const LAS float* s = scr + (8 * c) * 33 + n;
;         u32x4 o; o.x = cvt_pk_bf16(s[0 * 33], s[1 * 33]); o.y = cvt_pk_bf16(s[2 * 33], s[3 * 33]); o.z = cvt_pk_bf16(s[4 * 33], s[5 * 33]); o.w = cvt_pk_bf16(s[6 * 33], s[7 * 33]);
;         *(u32x4*)(WT + (size_t)(n0 + n) * ldt + coff + k0 + 8 * c) = o; }
;     asm volatile("s_waitcnt lgkmcnt(0)" ::: "memory");
; }
.LBB0_24:
	s_ashr_i32 s0, s10, 31
	s_lshr_b32 s0, s0, 26
	s_add_i32 s0, s10, s0
	s_ashr_i32 s13, s0, 6
	s_andn2_b32 s0, s0, 63
	s_lshl_b32 s1, s13, 11
	v_or_b32_e32 v26, s0, v1
	s_sub_i32 s14, s11, s1
	v_or_b32_e32 v28, 8, v26
	v_or_b32_e32 v30, 16, v26
	v_or_b32_e32 v32, 24, v26
	v_or_b32_e32 v34, 32, v26
	v_or_b32_e32 v36, 40, v26
	v_or_b32_e32 v38, 48, v26
	v_or_b32_e32 v40, 56, v26
	v_ashrrev_i32_e32 v27, 31, v26
	s_ashr_i32 s15, s14, 31
	v_ashrrev_i32_e32 v29, 31, v28
	v_ashrrev_i32_e32 v31, 31, v30
	v_ashrrev_i32_e32 v33, 31, v32
	v_ashrrev_i32_e32 v35, 31, v34
	v_ashrrev_i32_e32 v37, 31, v36
	v_ashrrev_i32_e32 v39, 31, v38
	v_ashrrev_i32_e32 v41, 31, v40
	v_lshlrev_b64 v[26:27], 13, v[26:27]
	v_lshl_add_u64 v[42:43], s[14:15], 2, v[6:7]
	v_lshlrev_b64 v[28:29], 13, v[28:29]
	v_lshlrev_b64 v[30:31], 13, v[30:31]
	v_lshlrev_b64 v[32:33], 13, v[32:33]
	v_lshlrev_b64 v[34:35], 13, v[34:35]
	v_lshlrev_b64 v[36:37], 13, v[36:37]
	v_lshlrev_b64 v[38:39], 13, v[38:39]
	v_lshlrev_b64 v[40:41], 13, v[40:41]
	v_lshl_add_u64 v[26:27], v[42:43], 0, v[26:27]
	v_lshl_add_u64 v[44:45], v[42:43], 0, v[28:29]
	v_lshl_add_u64 v[46:47], v[42:43], 0, v[30:31]
	v_lshl_add_u64 v[48:49], v[42:43], 0, v[32:33]
	v_lshl_add_u64 v[50:51], v[42:43], 0, v[34:35]
	v_lshl_add_u64 v[52:53], v[42:43], 0, v[36:37]
	v_lshl_add_u64 v[54:55], v[42:43], 0, v[38:39]
	v_lshl_add_u64 v[56:57], v[42:43], 0, v[40:41]
	global_load_dwordx4 v[26:29], v[26:27], off nt
	s_nop 0
	global_load_dwordx4 v[30:33], v[44:45], off nt
	global_load_dwordx4 v[34:37], v[46:47], off nt
	global_load_dwordx4 v[38:41], v[48:49], off nt
	s_nop 0
	global_load_dwordx4 v[42:45], v[50:51], off nt
	global_load_dwordx4 v[46:49], v[52:53], off nt
	s_nop 0
	global_load_dwordx4 v[50:53], v[54:55], off nt
	s_nop 0
	global_load_dwordx4 v[54:57], v[56:57], off nt
	s_mul_i32 s13, s13, 0xff400000
	s_ashr_i32 s1, s0, 31
	v_add_u32_e32 v60, s13, v3
	v_lshl_add_u64 v[58:59], s[0:1], 1, v[8:9]
	v_ashrrev_i32_e32 v61, 31, v60
	v_lshl_add_u64 v[66:67], v[58:59], 0, v[60:61]
	v_add_u32_e32 v62, 0xc000, v60
	v_ashrrev_i32_e32 v63, 31, v62
	v_lshl_add_u64 v[62:63], v[58:59], 0, v[62:63]
	v_add_u32_e32 v64, 0x18000, v60
	v_ashrrev_i32_e32 v65, 31, v64
	v_lshl_add_u64 v[64:65], v[58:59], 0, v[64:65]
	s_add_i32 s10, s10, s94
	s_add_i32 s11, s11, s12
	s_cmpk_gt_i32 s10, 0x3ff
	v_add_u32_e32 v3, s2, v3
	s_waitcnt vmcnt(7)
	ds_write2_b32 v17, v26, v27 offset1:1
	ds_write2_b32 v17, v28, v29 offset0:2 offset1:3
	s_waitcnt vmcnt(6)
	ds_write2_b32 v5, v30, v31 offset1:1
	ds_write2_b32 v10, v32, v33 offset1:1
	s_waitcnt vmcnt(5)
	ds_write2_b32 v11, v34, v35 offset1:1
	ds_write2_b32 v12, v36, v37 offset1:1
	s_waitcnt vmcnt(4)
	ds_write2_b32 v13, v38, v39 offset1:1
	ds_write2_b32 v14, v40, v41 offset1:1
	s_waitcnt vmcnt(3)
	ds_write2_b32 v15, v42, v43 offset1:1
	ds_write2_b32 v18, v44, v45 offset1:1
	s_waitcnt vmcnt(2)
	ds_write2_b32 v19, v46, v47 offset1:1
	ds_write2_b32 v20, v48, v49 offset1:1
	s_waitcnt vmcnt(1)
	ds_write2_b32 v21, v50, v51 offset1:1
	ds_write2_b32 v22, v52, v53 offset1:1
	s_waitcnt vmcnt(0)
	ds_write2_b32 v23, v54, v55 offset1:1
	ds_write2_b32 v24, v56, v57 offset1:1
	s_branch .Lrot24_mid
.Lrot24_top:
	s_mul_i32 s13, s13, 0xff400000
	s_ashr_i32 s1, s0, 31
	v_add_u32_e32 v60, s13, v3
	v_lshl_add_u64 v[58:59], s[0:1], 1, v[8:9]
	v_ashrrev_i32_e32 v61, 31, v60
	v_lshl_add_u64 v[66:67], v[58:59], 0, v[60:61]
	v_add_u32_e32 v62, 0xc000, v60
	v_ashrrev_i32_e32 v63, 31, v62
	v_lshl_add_u64 v[62:63], v[58:59], 0, v[62:63]
	v_add_u32_e32 v64, 0x18000, v60
	v_ashrrev_i32_e32 v65, 31, v64
	v_lshl_add_u64 v[64:65], v[58:59], 0, v[64:65]
	s_add_i32 s10, s10, s94
	s_add_i32 s11, s11, s12
	s_cmpk_gt_i32 s10, 0x3ff
	v_add_u32_e32 v3, s2, v3
	s_waitcnt vmcnt(11)
	ds_write2_b32 v17, v26, v27 offset1:1
	ds_write2_b32 v17, v28, v29 offset0:2 offset1:3
	s_waitcnt vmcnt(10)
	ds_write2_b32 v5, v30, v31 offset1:1
	ds_write2_b32 v10, v32, v33 offset1:1
	s_waitcnt vmcnt(9)
	ds_write2_b32 v11, v34, v35 offset1:1
	ds_write2_b32 v12, v36, v37 offset1:1
	s_waitcnt vmcnt(8)
	ds_write2_b32 v13, v38, v39 offset1:1
	ds_write2_b32 v14, v40, v41 offset1:1
	s_waitcnt vmcnt(7)
	ds_write2_b32 v15, v42, v43 offset1:1
	ds_write2_b32 v18, v44, v45 offset1:1
	s_waitcnt vmcnt(6)
	ds_write2_b32 v19, v46, v47 offset1:1
	ds_write2_b32 v20, v48, v49 offset1:1
	s_waitcnt vmcnt(5)
	ds_write2_b32 v21, v50, v51 offset1:1
	ds_write2_b32 v22, v52, v53 offset1:1
	s_waitcnt vmcnt(4)
	ds_write2_b32 v23, v54, v55 offset1:1
	ds_write2_b32 v24, v56, v57 offset1:1

; #define LAS __attribute__((address_space(3)))
; __device__ __forceinline__ unsigned cvt_pk_bf16(float lo, float hi) { unsigned r; asm volatile("v_cvt_pk_bf16_f32 %0, %1, %2" : "=v"(r) : "v"(lo), "v"(hi)); return r; }
; __device__ __forceinline__ void p0_transpose_item(const float* W, int N, bf16_t* WT, int ldt, int coff, LAS float* scr, int item, int lane) {
;     const int nblk = N / 32, kb = item / nblk, nb = item % nblk, k0 = 64 * kb, n0 = 32 * nb;
;     { f32x4 v[8];
; #pragma unroll
;       for (int i = 0; i < 8; ++i) v[i] = __builtin_nontemporal_load((const f32x4*)(W + (size_t)(k0 + 8 * i + (lane >> 3)) * N + n0 + 4 * (lane & 7)));
; #pragma unroll
;       for (int i = 0; i < 8; ++i) { LAS float* d = scr + (8 * i + (lane >> 3)) * 33 + 4 * (lane & 7); d[0] = v[i].x; d[1] = v[i].y; d[2] = v[i].z; d[3] = v[i].w; } }
;     asm volatile("s_waitcnt lgkmcnt(0)" ::: "memory");
;     const int c = lane & 7;
; #pragma unroll
;     for (int j = 0; j < 4; ++j) { const int n = (lane >> 3) + 8 * j; const LAS float* s = scr + (8 * c) * 33 + n;
;         u32x4 o; o.x = cvt_pk_bf16(s[0 * 33], s[1 * 33]); o.y = cvt_pk_bf16(s[2 * 33], s[3 * 33]); o.z = cvt_pk_bf16(s[4 * 33], s[5 * 33]); o.w = cvt_pk_bf16(s[6 * 33], s[7 * 33]);
;         *(u32x4*)(WT + (size_t)(n0 + n) * ldt + coff + k0 + 8 * c) = o; }
;     asm volatile("s_waitcnt lgkmcnt(0)" ::: "memory");
; }
.Lrot24_nonext:
	ds_read2_b32 v[92:93], v16 offset1:33
	ds_read2_b32 v[94:95], v16 offset0:66 offset1:99
	ds_read2_b32 v[96:97], v16 offset0:132 offset1:165
	ds_read2_b32 v[98:99], v16 offset0:198 offset1:231
	ds_read2_b32 v[100:101], v16 offset0:8 offset1:41
	ds_read2_b32 v[102:103], v16 offset0:74 offset1:107
	ds_read2_b32 v[104:105], v16 offset0:140 offset1:173
	ds_read2_b32 v[106:107], v16 offset0:206 offset1:239
	ds_read2_b32 v[108:109], v16 offset0:16 offset1:49
	ds_read2_b32 v[110:111], v16 offset0:82 offset1:115
	ds_read2_b32 v[112:113], v16 offset0:148 offset1:181
	ds_read2_b32 v[114:115], v16 offset0:214 offset1:247
	ds_read2_b32 v[116:117], v16 offset0:24 offset1:57
	ds_read2_b32 v[118:119], v16 offset0:90 offset1:123
	ds_read2_b32 v[120:121], v16 offset0:156 offset1:189
	ds_read2_b32 v[122:123], v16 offset0:222 offset1:255
	s_waitcnt lgkmcnt(0)
	s_nop 0
	v_cvt_pk_bf16_f32 v126, v92, v93
	s_nop 0
	v_cvt_pk_bf16_f32 v127, v94, v95
	s_nop 0
	v_cvt_pk_bf16_f32 v128, v96, v97
	s_nop 0
	v_cvt_pk_bf16_f32 v129, v98, v99
	global_store_dwordx4 v[66:67], v[126:129], off
	v_add_u32_e32 v132, 0x24000, v60
	v_ashrrev_i32_e32 v133, 31, v132
	s_nop 0
	v_cvt_pk_bf16_f32 v126, v100, v101
	s_nop 0
	v_cvt_pk_bf16_f32 v127, v102, v103
	s_nop 0
	v_cvt_pk_bf16_f32 v128, v104, v105
	s_nop 0
	v_cvt_pk_bf16_f32 v129, v106, v107
	global_store_dwordx4 v[62:63], v[126:129], off
	v_lshl_add_u64 v[132:133], v[58:59], 0, v[132:133]
	s_nop 0
	v_cvt_pk_bf16_f32 v126, v108, v109
	s_nop 0
	v_cvt_pk_bf16_f32 v127, v110, v111
	s_nop 0
	v_cvt_pk_bf16_f32 v128, v112, v113
	s_nop 0
	v_cvt_pk_bf16_f32 v129, v114, v115
	global_store_dwordx4 v[64:65], v[126:129], off
	s_nop 0
	s_nop 0
	v_cvt_pk_bf16_f32 v126, v116, v117
	s_nop 0
	v_cvt_pk_bf16_f32 v127, v118, v119
	s_nop 0
	v_cvt_pk_bf16_f32 v128, v120, v121
	s_nop 0
	v_cvt_pk_bf16_f32 v129, v122, v123
	global_store_dwordx4 v[132:133], v[126:129], off
	s_waitcnt lgkmcnt(0)
	s_cmpk_gt_i32 s10, 0x3ff
	s_cbranch_scc0 .Lrot24_top

; #define LAS __attribute__((address_space(3)))
; __device__ __forceinline__ unsigned cvt_pk_bf16(float lo, float hi) { unsigned r; asm volatile("v_cvt_pk_bf16_f32 %0, %1, %2" : "=v"(r) : "v"(lo), "v"(hi)); return r; }
; __device__ __forceinline__ void p0_transpose_item(const float* W, int N, bf16_t* WT, int ldt, int coff, LAS float* scr, int item, int lane) {
;     const int nblk = N / 32, kb = item / nblk, nb = item % nblk, k0 = 64 * kb, n0 = 32 * nb;
;     { f32x4 v[8];
; #pragma unroll
;       for (int i = 0; i < 8; ++i) v[i] = __builtin_nontemporal_load((const f32x4*)(W + (size_t)(k0 + 8 * i + (lane >> 3)) * N + n0 + 4 * (lane & 7)));
; #pragma unroll
;       for (int i = 0; i < 8; ++i) { LAS float* d = scr + (8 * i + (lane >> 3)) * 33 + 4 * (lane & 7); d[0] = v[i].x; d[1] = v[i].y; d[2] = v[i].z; d[3] = v[i].w; } }
;     asm volatile("s_waitcnt lgkmcnt(0)" ::: "memory");
;     const int c = lane & 7;
; #pragma unroll
;     for (int j = 0; j < 4; ++j) { const int n = (lane >> 3) + 8 * j; const LAS float* s = scr + (8 * c) * 33 + n;
;         u32x4 o; o.x = cvt_pk_bf16(s[0 * 33], s[1 * 33]); o.y = cvt_pk_bf16(s[2 * 33], s[3 * 33]); o.z = cvt_pk_bf16(s[4 * 33], s[5 * 33]); o.w = cvt_pk_bf16(s[6 * 33], s[7 * 33]);
;         *(u32x4*)(WT + (size_t)(n0 + n) * ldt + coff + k0 + 8 * c) = o; }
;     asm volatile("s_waitcnt lgkmcnt(0)" ::: "memory");
; }
.LBB0_30:
	s_ashr_i32 s0, s11, 31
	s_lshr_b32 s0, s0, 24
	s_add_i32 s0, s11, s0
	s_ashr_i32 s0, s0, 8
	s_lshl_b32 s2, s0, 6
	s_lshl_b32 s0, s0, 13
	v_or_b32_e32 v24, s2, v1
	s_sub_i32 s0, s12, s0
	v_or_b32_e32 v26, 8, v24
	v_or_b32_e32 v28, 16, v24
	v_or_b32_e32 v30, 24, v24
	v_or_b32_e32 v32, 32, v24
	v_or_b32_e32 v34, 40, v24
	v_or_b32_e32 v36, 48, v24
	v_or_b32_e32 v38, 56, v24
	s_ashr_i32 s1, s0, 31
	v_ashrrev_i32_e32 v25, 31, v24
	v_ashrrev_i32_e32 v27, 31, v26
	v_ashrrev_i32_e32 v29, 31, v28
	v_ashrrev_i32_e32 v31, 31, v30
	v_ashrrev_i32_e32 v33, 31, v32
	v_ashrrev_i32_e32 v35, 31, v34
	v_ashrrev_i32_e32 v37, 31, v36
	v_ashrrev_i32_e32 v39, 31, v38
	v_lshl_add_u64 v[40:41], s[0:1], 2, v[6:7]
	v_lshlrev_b64 v[24:25], 15, v[24:25]
	v_lshlrev_b64 v[42:43], 15, v[26:27]
	v_lshlrev_b64 v[28:29], 15, v[28:29]
	v_lshlrev_b64 v[30:31], 15, v[30:31]
	v_lshlrev_b64 v[32:33], 15, v[32:33]
	v_lshlrev_b64 v[34:35], 15, v[34:35]
	v_lshlrev_b64 v[36:37], 15, v[36:37]
	v_lshlrev_b64 v[38:39], 15, v[38:39]
	v_lshl_add_u64 v[24:25], v[40:41], 0, v[24:25]
	v_lshl_add_u64 v[42:43], v[40:41], 0, v[42:43]
	v_lshl_add_u64 v[44:45], v[40:41], 0, v[28:29]
	v_lshl_add_u64 v[46:47], v[40:41], 0, v[30:31]
	v_lshl_add_u64 v[48:49], v[40:41], 0, v[32:33]
	v_lshl_add_u64 v[50:51], v[40:41], 0, v[34:35]
	v_lshl_add_u64 v[52:53], v[40:41], 0, v[36:37]
	v_lshl_add_u64 v[54:55], v[40:41], 0, v[38:39]
	global_load_dwordx4 v[24:27], v[24:25], off nt
	s_nop 0
	global_load_dwordx4 v[28:31], v[42:43], off nt
	global_load_dwordx4 v[32:35], v[44:45], off nt
	global_load_dwordx4 v[36:39], v[46:47], off nt
	s_nop 0
	global_load_dwordx4 v[40:43], v[48:49], off nt
	global_load_dwordx4 v[44:47], v[50:51], off nt
	s_nop 0
	global_load_dwordx4 v[48:51], v[52:53], off nt
	s_nop 0
	global_load_dwordx4 v[52:55], v[54:55], off nt
	v_add_u32_e32 v58, s0, v1
	s_ashr_i32 s3, s2, 31
	v_ashrrev_i32_e32 v59, 31, v58
	v_lshl_add_u64 v[56:57], s[2:3], 1, v[8:9]
	v_lshlrev_b64 v[64:65], 12, v[58:59]
	v_add_u32_e32 v60, 8, v58
	v_lshl_add_u64 v[64:65], v[56:57], 0, v[64:65]
	v_ashrrev_i32_e32 v61, 31, v60
	v_lshlrev_b64 v[60:61], 12, v[60:61]
	v_add_u32_e32 v62, 16, v58
	v_lshl_add_u64 v[60:61], v[56:57], 0, v[60:61]
	v_ashrrev_i32_e32 v63, 31, v62
	v_lshlrev_b64 v[62:63], 12, v[62:63]
	v_lshl_add_u64 v[62:63], v[56:57], 0, v[62:63]
	s_add_i32 s11, s11, s94
	s_add_i32 s12, s12, s13
	s_cmpk_gt_i32 s11, 0x1fff
	s_waitcnt vmcnt(7)
	ds_write2_b32 v17, v24, v25 offset1:1
	ds_write2_b32 v17, v26, v27 offset0:2 offset1:3
	s_waitcnt vmcnt(6)
	ds_write2_b32 v3, v28, v29 offset1:1
	ds_write2_b32 v5, v30, v31 offset1:1
	s_waitcnt vmcnt(5)
	ds_write2_b32 v10, v32, v33 offset1:1
	ds_write2_b32 v11, v34, v35 offset1:1
	s_waitcnt vmcnt(4)
	ds_write2_b32 v12, v36, v37 offset1:1
	ds_write2_b32 v13, v38, v39 offset1:1
	s_waitcnt vmcnt(3)
	ds_write2_b32 v14, v40, v41 offset1:1
	ds_write2_b32 v15, v42, v43 offset1:1
	s_waitcnt vmcnt(2)
	ds_write2_b32 v18, v44, v45 offset1:1
	ds_write2_b32 v19, v46, v47 offset1:1
	s_waitcnt vmcnt(1)
	ds_write2_b32 v20, v48, v49 offset1:1
	ds_write2_b32 v21, v50, v51 offset1:1
	s_waitcnt vmcnt(0)
	ds_write2_b32 v22, v52, v53 offset1:1
	ds_write2_b32 v23, v54, v55 offset1:1
	s_branch .Lrot30_mid
.Lrot30_top:
	v_add_u32_e32 v58, s0, v1
	s_ashr_i32 s3, s2, 31
	v_ashrrev_i32_e32 v59, 31, v58
	v_lshl_add_u64 v[56:57], s[2:3], 1, v[8:9]
	v_lshlrev_b64 v[64:65], 12, v[58:59]
	v_add_u32_e32 v60, 8, v58
	v_lshl_add_u64 v[64:65], v[56:57], 0, v[64:65]
	v_ashrrev_i32_e32 v61, 31, v60
	v_lshlrev_b64 v[60:61], 12, v[60:61]
	v_add_u32_e32 v62, 16, v58
	v_lshl_add_u64 v[60:61], v[56:57], 0, v[60:61]
	v_ashrrev_i32_e32 v63, 31, v62
	v_lshlrev_b64 v[62:63], 12, v[62:63]
	v_lshl_add_u64 v[62:63], v[56:57], 0, v[62:63]
	s_add_i32 s11, s11, s94
	s_add_i32 s12, s12, s13
	s_cmpk_gt_i32 s11, 0x1fff
	s_waitcnt vmcnt(11)
	ds_write2_b32 v17, v24, v25 offset1:1
	ds_write2_b32 v17, v26, v27 offset0:2 offset1:3
	s_waitcnt vmcnt(10)
	ds_write2_b32 v3, v28, v29 offset1:1
	ds_write2_b32 v5, v30, v31 offset1:1
	s_waitcnt vmcnt(9)
	ds_write2_b32 v10, v32, v33 offset1:1
	ds_write2_b32 v11, v34, v35 offset1:1
	s_waitcnt vmcnt(8)
	ds_write2_b32 v12, v36, v37 offset1:1
	ds_write2_b32 v13, v38, v39 offset1:1
	s_waitcnt vmcnt(7)
	ds_write2_b32 v14, v40, v41 offset1:1
	ds_write2_b32 v15, v42, v43 offset1:1
	s_waitcnt vmcnt(6)
	ds_write2_b32 v18, v44, v45 offset1:1
	ds_write2_b32 v19, v46, v47 offset1:1
	s_waitcnt vmcnt(5)
	ds_write2_b32 v20, v48, v49 offset1:1
	ds_write2_b32 v21, v50, v51 offset1:1
	s_waitcnt vmcnt(4)
	ds_write2_b32 v22, v52, v53 offset1:1
	ds_write2_b32 v23, v54, v55 offset1:1
; #define LAS __attribute__((address_space(3)))
; __device__ __forceinline__ unsigned cvt_pk_bf16(float lo, float hi) { unsigned r; asm volatile("v_cvt_pk_bf16_f32 %0, %1, %2" : "=v"(r) : "v"(lo), "v"(hi)); return r; }
; __device__ __forceinline__ void p0_transpose_item(const float* W, int N, bf16_t* WT, int ldt, int coff, LAS float* scr, int item, int lane) {
;     const int nblk = N / 32, kb = item / nblk, nb = item % nblk, k0 = 64 * kb, n0 = 32 * nb;
;     { f32x4 v[8];
; #pragma unroll
;       for (int i = 0; i < 8; ++i) v[i] = __builtin_nontemporal_load((const f32x4*)(W + (size_t)(k0 + 8 * i + (lane >> 3)) * N + n0 + 4 * (lane & 7)));
; #pragma unroll
;       for (int i = 0; i < 8; ++i) { LAS float* d = scr + (8 * i + (lane >> 3)) * 33 + 4 * (lane & 7); d[0] = v[i].x; d[1] = v[i].y; d[2] = v[i].z; d[3] = v[i].w; } }
;     asm volatile("s_waitcnt lgkmcnt(0)" ::: "memory");
;     const int c = lane & 7;
; #pragma unroll
;     for (int j = 0; j < 4; ++j) { const int n = (lane >> 3) + 8 * j; const LAS float* s = scr + (8 * c) * 33 + n;
;         u32x4 o; o.x = cvt_pk_bf16(s[0 * 33], s[1 * 33]); o.y = cvt_pk_bf16(s[2 * 33], s[3 * 33]); o.z = cvt_pk_bf16(s[4 * 33], s[5 * 33]); o.w = cvt_pk_bf16(s[6 * 33], s[7 * 33]);
;         *(u32x4*)(WT + (size_t)(n0 + n) * ldt + coff + k0 + 8 * c) = o; }
;     asm volatile("s_waitcnt lgkmcnt(0)" ::: "memory");
; }
.Lrot30_mid:
	s_waitcnt lgkmcnt(0)
	s_cbranch_scc1 .Lrot30_nonext
	s_ashr_i32 s0, s11, 31
	s_lshr_b32 s0, s0, 24
	s_add_i32 s0, s11, s0
	s_ashr_i32 s0, s0, 8
	s_lshl_b32 s2, s0, 6
	s_lshl_b32 s0, s0, 13
	v_or_b32_e32 v24, s2, v1
	s_sub_i32 s0, s12, s0
	v_or_b32_e32 v26, 8, v24
	v_or_b32_e32 v28, 16, v24
	v_or_b32_e32 v30, 24, v24
	v_or_b32_e32 v32, 32, v24
	v_or_b32_e32 v34, 40, v24
	v_or_b32_e32 v36, 48, v24
	v_or_b32_e32 v38, 56, v24
	s_ashr_i32 s1, s0, 31
	v_ashrrev_i32_e32 v25, 31, v24
	v_ashrrev_i32_e32 v27, 31, v26
	v_ashrrev_i32_e32 v29, 31, v28
	v_ashrrev_i32_e32 v31, 31, v30
	v_ashrrev_i32_e32 v33, 31, v32
	v_ashrrev_i32_e32 v35, 31, v34
	v_ashrrev_i32_e32 v37, 31, v36
	v_ashrrev_i32_e32 v39, 31, v38
	v_lshl_add_u64 v[40:41], s[0:1], 2, v[6:7]
	v_lshlrev_b64 v[24:25], 15, v[24:25]
	v_lshlrev_b64 v[42:43], 15, v[26:27]
	v_lshlrev_b64 v[28:29], 15, v[28:29]
	v_lshlrev_b64 v[30:31], 15, v[30:31]
	v_lshlrev_b64 v[32:33], 15, v[32:33]
	v_lshlrev_b64 v[34:35], 15, v[34:35]
	v_lshlrev_b64 v[36:37], 15, v[36:37]
	v_lshlrev_b64 v[38:39], 15, v[38:39]
	v_lshl_add_u64 v[24:25], v[40:41], 0, v[24:25]
	v_lshl_add_u64 v[42:43], v[40:41], 0, v[42:43]
	v_lshl_add_u64 v[44:45], v[40:41], 0, v[28:29]
	v_lshl_add_u64 v[46:47], v[40:41], 0, v[30:31]
	v_lshl_add_u64 v[48:49], v[40:41], 0, v[32:33]
	v_lshl_add_u64 v[50:51], v[40:41], 0, v[34:35]
	v_lshl_add_u64 v[52:53], v[40:41], 0, v[36:37]
	v_lshl_add_u64 v[54:55], v[40:41], 0, v[38:39]
	global_load_dwordx4 v[24:27], v[24:25], off nt
	s_nop 0
	global_load_dwordx4 v[28:31], v[42:43], off nt
	global_load_dwordx4 v[32:35], v[44:45], off nt
	global_load_dwordx4 v[36:39], v[46:47], off nt
	s_nop 0
	global_load_dwordx4 v[40:43], v[48:49], off nt
	global_load_dwordx4 v[44:47], v[50:51], off nt
	s_nop 0
	global_load_dwordx4 v[48:51], v[52:53], off nt
	s_nop 0
	global_load_dwordx4 v[52:55], v[54:55], off nt
.Lrot30_nonext:
	ds_read2_b32 v[92:93], v16 offset1:33
	ds_read2_b32 v[94:95], v16 offset0:66 offset1:99
	ds_read2_b32 v[96:97], v16 offset0:132 offset1:165
	ds_read2_b32 v[98:99], v16 offset0:198 offset1:231
	ds_read2_b32 v[100:101], v16 offset0:8 offset1:41
	ds_read2_b32 v[102:103], v16 offset0:74 offset1:107
	ds_read2_b32 v[104:105], v16 offset0:140 offset1:173
	ds_read2_b32 v[106:107], v16 offset0:206 offset1:239
	ds_read2_b32 v[108:109], v16 offset0:16 offset1:49
	ds_read2_b32 v[110:111], v16 offset0:82 offset1:115
	ds_read2_b32 v[112:113], v16 offset0:148 offset1:181
	ds_read2_b32 v[114:115], v16 offset0:214 offset1:247
	ds_read2_b32 v[116:117], v16 offset0:24 offset1:57
	ds_read2_b32 v[118:119], v16 offset0:90 offset1:123
	ds_read2_b32 v[120:121], v16 offset0:156 offset1:189
	ds_read2_b32 v[122:123], v16 offset0:222 offset1:255
	s_waitcnt lgkmcnt(0)
	s_nop 0
	v_cvt_pk_bf16_f32 v124, v92, v93
	s_nop 0
	v_cvt_pk_bf16_f32 v125, v94, v95
	s_nop 0
	v_cvt_pk_bf16_f32 v126, v96, v97
	s_nop 0
	v_cvt_pk_bf16_f32 v127, v98, v99
	global_store_dwordx4 v[64:65], v[124:127], off
	v_add_u32_e32 v130, 24, v58
	v_ashrrev_i32_e32 v131, 31, v130
	s_nop 0
	v_cvt_pk_bf16_f32 v124, v100, v101
	s_nop 0
	v_cvt_pk_bf16_f32 v125, v102, v103
	s_nop 0
	v_cvt_pk_bf16_f32 v126, v104, v105
	s_nop 0
	v_cvt_pk_bf16_f32 v127, v106, v107
	global_store_dwordx4 v[60:61], v[124:127], off
	v_lshlrev_b64 v[130:131], 12, v[130:131]
	v_lshl_add_u64 v[130:131], v[56:57], 0, v[130:131]
	s_nop 0
	v_cvt_pk_bf16_f32 v124, v108, v109
	s_nop 0
	v_cvt_pk_bf16_f32 v125, v110, v111
	s_nop 0
	v_cvt_pk_bf16_f32 v126, v112, v113
	s_nop 0
	v_cvt_pk_bf16_f32 v127, v114, v115
	global_store_dwordx4 v[62:63], v[124:127], off
	s_nop 0
	s_nop 0
	v_cvt_pk_bf16_f32 v124, v116, v117
	s_nop 0
	v_cvt_pk_bf16_f32 v125, v118, v119
	s_nop 0
	v_cvt_pk_bf16_f32 v126, v120, v121
	s_nop 0
	v_cvt_pk_bf16_f32 v127, v122, v123
	global_store_dwordx4 v[130:131], v[124:127], off
	s_waitcnt lgkmcnt(0)
	s_cmpk_gt_i32 s11, 0x1fff
	s_cbranch_scc0 .Lrot30_top

; #define LAS __attribute__((address_space(3)))
; __device__ __forceinline__ unsigned cvt_pk_bf16(float lo, float hi) { unsigned r; asm volatile("v_cvt_pk_bf16_f32 %0, %1, %2" : "=v"(r) : "v"(lo), "v"(hi)); return r; }
; __device__ __forceinline__ void p0_transpose_item(const float* W, int N, bf16_t* WT, int ldt, int coff, LAS float* scr, int item, int lane) {
;     const int nblk = N / 32, kb = item / nblk, nb = item % nblk, k0 = 64 * kb, n0 = 32 * nb;
;     { f32x4 v[8];
; #pragma unroll
;       for (int i = 0; i < 8; ++i) v[i] = __builtin_nontemporal_load((const f32x4*)(W + (size_t)(k0 + 8 * i + (lane >> 3)) * N + n0 + 4 * (lane & 7)));
; #pragma unroll
;       for (int i = 0; i < 8; ++i) { LAS float* d = scr + (8 * i + (lane >> 3)) * 33 + 4 * (lane & 7); d[0] = v[i].x; d[1] = v[i].y; d[2] = v[i].z; d[3] = v[i].w; } }
;     asm volatile("s_waitcnt lgkmcnt(0)" ::: "memory");
;     const int c = lane & 7;
; #pragma unroll
;     for (int j = 0; j < 4; ++j) { const int n = (lane >> 3) + 8 * j; const LAS float* s = scr + (8 * c) * 33 + n;
;         u32x4 o; o.x = cvt_pk_bf16(s[0 * 33], s[1 * 33]); o.y = cvt_pk_bf16(s[2 * 33], s[3 * 33]); o.z = cvt_pk_bf16(s[4 * 33], s[5 * 33]); o.w = cvt_pk_bf16(s[6 * 33], s[7 * 33]);
;         *(u32x4*)(WT + (size_t)(n0 + n) * ldt + coff + k0 + 8 * c) = o; }
;     asm volatile("s_waitcnt lgkmcnt(0)" ::: "memory");
; }
.LBB0_33:
	s_ashr_i32 s0, s8, 31
	s_lshr_b32 s0, s0, 26
	s_add_i32 s0, s8, s0
	s_and_b32 s2, s0, 0xffffffc0
	s_lshl_b32 s0, s0, 5
	s_and_b32 s0, s0, 0xfffff800
	v_or_b32_e32 v24, s2, v1
	s_sub_i32 s0, s9, s0
	v_or_b32_e32 v26, 8, v24
	v_or_b32_e32 v28, 16, v24
	v_or_b32_e32 v30, 24, v24
	v_or_b32_e32 v32, 32, v24
	v_or_b32_e32 v34, 40, v24
	v_or_b32_e32 v36, 48, v24
	v_or_b32_e32 v38, 56, v24
	v_ashrrev_i32_e32 v25, 31, v24
	s_ashr_i32 s1, s0, 31
	v_ashrrev_i32_e32 v27, 31, v26
	v_ashrrev_i32_e32 v29, 31, v28
	v_ashrrev_i32_e32 v31, 31, v30
	v_ashrrev_i32_e32 v33, 31, v32
	v_ashrrev_i32_e32 v35, 31, v34
	v_ashrrev_i32_e32 v37, 31, v36
	v_ashrrev_i32_e32 v39, 31, v38
	v_lshlrev_b64 v[24:25], 13, v[24:25]
	v_lshl_add_u64 v[40:41], s[0:1], 2, v[6:7]
	v_lshlrev_b64 v[26:27], 13, v[26:27]
	v_lshlrev_b64 v[28:29], 13, v[28:29]
	v_lshlrev_b64 v[30:31], 13, v[30:31]
	v_lshlrev_b64 v[32:33], 13, v[32:33]
	v_lshlrev_b64 v[34:35], 13, v[34:35]
	v_lshlrev_b64 v[36:37], 13, v[36:37]
	v_lshlrev_b64 v[38:39], 13, v[38:39]
	v_lshl_add_u64 v[24:25], v[40:41], 0, v[24:25]
	v_lshl_add_u64 v[42:43], v[40:41], 0, v[26:27]
	v_lshl_add_u64 v[44:45], v[40:41], 0, v[28:29]
	v_lshl_add_u64 v[46:47], v[40:41], 0, v[30:31]
	v_lshl_add_u64 v[48:49], v[40:41], 0, v[32:33]
	v_lshl_add_u64 v[50:51], v[40:41], 0, v[34:35]
	v_lshl_add_u64 v[52:53], v[40:41], 0, v[36:37]
	v_lshl_add_u64 v[54:55], v[40:41], 0, v[38:39]
	global_load_dwordx4 v[24:27], v[24:25], off nt
	s_nop 0
	global_load_dwordx4 v[28:31], v[42:43], off nt
	global_load_dwordx4 v[32:35], v[44:45], off nt
	global_load_dwordx4 v[36:39], v[46:47], off nt
	s_nop 0
	global_load_dwordx4 v[40:43], v[48:49], off nt
	global_load_dwordx4 v[44:47], v[50:51], off nt
	s_nop 0
	global_load_dwordx4 v[48:51], v[52:53], off nt
	s_nop 0
	global_load_dwordx4 v[52:55], v[54:55], off nt
	v_add_u32_e32 v58, s0, v1
	s_ashr_i32 s3, s2, 31
	v_ashrrev_i32_e32 v59, 31, v58
	v_lshl_add_u64 v[56:57], s[2:3], 1, v[8:9]
	v_lshlrev_b64 v[64:65], 14, v[58:59]
	v_add_u32_e32 v60, 8, v58
	v_lshl_add_u64 v[64:65], v[56:57], 0, v[64:65]
	v_ashrrev_i32_e32 v61, 31, v60
	v_lshlrev_b64 v[60:61], 14, v[60:61]
	v_add_u32_e32 v62, 16, v58
	v_lshl_add_u64 v[60:61], v[56:57], 0, v[60:61]
	v_ashrrev_i32_e32 v63, 31, v62
	v_lshlrev_b64 v[62:63], 14, v[62:63]
	v_lshl_add_u64 v[62:63], v[56:57], 0, v[62:63]
	s_add_i32 s8, s8, s94
	s_add_i32 s9, s9, s10
	s_cmpk_gt_i32 s8, 0x1fff
	s_waitcnt vmcnt(7)
	ds_write2_b32 v17, v24, v25 offset1:1
	ds_write2_b32 v17, v26, v27 offset0:2 offset1:3
	s_waitcnt vmcnt(6)
	ds_write2_b32 v3, v28, v29 offset1:1
	ds_write2_b32 v5, v30, v31 offset1:1
	s_waitcnt vmcnt(5)
	ds_write2_b32 v10, v32, v33 offset1:1
	ds_write2_b32 v11, v34, v35 offset1:1
	s_waitcnt vmcnt(4)
	ds_write2_b32 v12, v36, v37 offset1:1
	ds_write2_b32 v13, v38, v39 offset1:1
	s_waitcnt vmcnt(3)
	ds_write2_b32 v14, v40, v41 offset1:1
	ds_write2_b32 v15, v42, v43 offset1:1
	s_waitcnt vmcnt(2)
	ds_write2_b32 v18, v44, v45 offset1:1
	ds_write2_b32 v19, v46, v47 offset1:1
	s_waitcnt vmcnt(1)
	ds_write2_b32 v20, v48, v49 offset1:1
	ds_write2_b32 v21, v50, v51 offset1:1
	s_waitcnt vmcnt(0)
	ds_write2_b32 v22, v52, v53 offset1:1
	ds_write2_b32 v23, v54, v55 offset1:1
	s_branch .Lrot33_mid
.Lrot33_top:
	v_add_u32_e32 v58, s0, v1
	s_ashr_i32 s3, s2, 31
	v_ashrrev_i32_e32 v59, 31, v58
	v_lshl_add_u64 v[56:57], s[2:3], 1, v[8:9]
	v_lshlrev_b64 v[64:65], 14, v[58:59]
	v_add_u32_e32 v60, 8, v58
	v_lshl_add_u64 v[64:65], v[56:57], 0, v[64:65]
	v_ashrrev_i32_e32 v61, 31, v60
	v_lshlrev_b64 v[60:61], 14, v[60:61]
	v_add_u32_e32 v62, 16, v58
	v_lshl_add_u64 v[60:61], v[56:57], 0, v[60:61]
	v_ashrrev_i32_e32 v63, 31, v62
	v_lshlrev_b64 v[62:63], 14, v[62:63]
	v_lshl_add_u64 v[62:63], v[56:57], 0, v[62:63]
	s_add_i32 s8, s8, s94
	s_add_i32 s9, s9, s10
	s_cmpk_gt_i32 s8, 0x1fff
	s_waitcnt vmcnt(11)
	ds_write2_b32 v17, v24, v25 offset1:1
	ds_write2_b32 v17, v26, v27 offset0:2 offset1:3
	s_waitcnt vmcnt(10)
	ds_write2_b32 v3, v28, v29 offset1:1
	ds_write2_b32 v5, v30, v31 offset1:1
	s_waitcnt vmcnt(9)
	ds_write2_b32 v10, v32, v33 offset1:1
	ds_write2_b32 v11, v34, v35 offset1:1
	s_waitcnt vmcnt(8)
	ds_write2_b32 v12, v36, v37 offset1:1
	ds_write2_b32 v13, v38, v39 offset1:1
	s_waitcnt vmcnt(7)
	ds_write2_b32 v14, v40, v41 offset1:1
	ds_write2_b32 v15, v42, v43 offset1:1
	s_waitcnt vmcnt(6)
	ds_write2_b32 v18, v44, v45 offset1:1
	ds_write2_b32 v19, v46, v47 offset1:1
	s_waitcnt vmcnt(5)
	ds_write2_b32 v20, v48, v49 offset1:1
	ds_write2_b32 v21, v50, v51 offset1:1
	s_waitcnt vmcnt(4)
	ds_write2_b32 v22, v52, v53 offset1:1
	ds_write2_b32 v23, v54, v55 offset1:1
; #define LAS __attribute__((address_space(3)))
; __device__ __forceinline__ unsigned cvt_pk_bf16(float lo, float hi) { unsigned r; asm volatile("v_cvt_pk_bf16_f32 %0, %1, %2" : "=v"(r) : "v"(lo), "v"(hi)); return r; }
; __device__ __forceinline__ void p0_transpose_item(const float* W, int N, bf16_t* WT, int ldt, int coff, LAS float* scr, int item, int lane) {
;     const int nblk = N / 32, kb = item / nblk, nb = item % nblk, k0 = 64 * kb, n0 = 32 * nb;
;     { f32x4 v[8];
; #pragma unroll
;       for (int i = 0; i < 8; ++i) v[i] = __builtin_nontemporal_load((const f32x4*)(W + (size_t)(k0 + 8 * i + (lane >> 3)) * N + n0 + 4 * (lane & 7)));
; #pragma unroll
;       for (int i = 0; i < 8; ++i) { LAS float* d = scr + (8 * i + (lane >> 3)) * 33 + 4 * (lane & 7); d[0] = v[i].x; d[1] = v[i].y; d[2] = v[i].z; d[3] = v[i].w; } }
;     asm volatile("s_waitcnt lgkmcnt(0)" ::: "memory");
;     const int c = lane & 7;
; #pragma unroll
;     for (int j = 0; j < 4; ++j) { const int n = (lane >> 3) + 8 * j; const LAS float* s = scr + (8 * c) * 33 + n;
;         u32x4 o; o.x = cvt_pk_bf16(s[0 * 33], s[1 * 33]); o.y = cvt_pk_bf16(s[2 * 33], s[3 * 33]); o.z = cvt_pk_bf16(s[4 * 33], s[5 * 33]); o.w = cvt_pk_bf16(s[6 * 33], s[7 * 33]);
;         *(u32x4*)(WT + (size_t)(n0 + n) * ldt + coff + k0 + 8 * c) = o; }
;     asm volatile("s_waitcnt lgkmcnt(0)" ::: "memory");
; }
.Lrot33_mid:
	s_waitcnt lgkmcnt(0)
	s_cbranch_scc1 .Lrot33_nonext
	s_ashr_i32 s0, s8, 31
	s_lshr_b32 s0, s0, 26
	s_add_i32 s0, s8, s0
	s_and_b32 s2, s0, 0xffffffc0
	s_lshl_b32 s0, s0, 5
	s_and_b32 s0, s0, 0xfffff800
	v_or_b32_e32 v24, s2, v1
	s_sub_i32 s0, s9, s0
	v_or_b32_e32 v26, 8, v24
	v_or_b32_e32 v28, 16, v24
	v_or_b32_e32 v30, 24, v24
	v_or_b32_e32 v32, 32, v24
	v_or_b32_e32 v34, 40, v24
	v_or_b32_e32 v36, 48, v24
	v_or_b32_e32 v38, 56, v24
	v_ashrrev_i32_e32 v25, 31, v24
	s_ashr_i32 s1, s0, 31
	v_ashrrev_i32_e32 v27, 31, v26
	v_ashrrev_i32_e32 v29, 31, v28
	v_ashrrev_i32_e32 v31, 31, v30
	v_ashrrev_i32_e32 v33, 31, v32
	v_ashrrev_i32_e32 v35, 31, v34
	v_ashrrev_i32_e32 v37, 31, v36
	v_ashrrev_i32_e32 v39, 31, v38
	v_lshlrev_b64 v[24:25], 13, v[24:25]
	v_lshl_add_u64 v[40:41], s[0:1], 2, v[6:7]
	v_lshlrev_b64 v[26:27], 13, v[26:27]
	v_lshlrev_b64 v[28:29], 13, v[28:29]
	v_lshlrev_b64 v[30:31], 13, v[30:31]
	v_lshlrev_b64 v[32:33], 13, v[32:33]
	v_lshlrev_b64 v[34:35], 13, v[34:35]
	v_lshlrev_b64 v[36:37], 13, v[36:37]
	v_lshlrev_b64 v[38:39], 13, v[38:39]
	v_lshl_add_u64 v[24:25], v[40:41], 0, v[24:25]
	v_lshl_add_u64 v[42:43], v[40:41], 0, v[26:27]
	v_lshl_add_u64 v[44:45], v[40:41], 0, v[28:29]
	v_lshl_add_u64 v[46:47], v[40:41], 0, v[30:31]
	v_lshl_add_u64 v[48:49], v[40:41], 0, v[32:33]
	v_lshl_add_u64 v[50:51], v[40:41], 0, v[34:35]
	v_lshl_add_u64 v[52:53], v[40:41], 0, v[36:37]
	v_lshl_add_u64 v[54:55], v[40:41], 0, v[38:39]
	global_load_dwordx4 v[24:27], v[24:25], off nt
	s_nop 0
	global_load_dwordx4 v[28:31], v[42:43], off nt
	global_load_dwordx4 v[32:35], v[44:45], off nt
	global_load_dwordx4 v[36:39], v[46:47], off nt
	s_nop 0
	global_load_dwordx4 v[40:43], v[48:49], off nt
	global_load_dwordx4 v[44:47], v[50:51], off nt
	s_nop 0
	global_load_dwordx4 v[48:51], v[52:53], off nt
	s_nop 0
	global_load_dwordx4 v[52:55], v[54:55], off nt
.Lrot33_nonext:
	ds_read2_b32 v[92:93], v16 offset1:33
	ds_read2_b32 v[94:95], v16 offset0:66 offset1:99
	ds_read2_b32 v[96:97], v16 offset0:132 offset1:165
	ds_read2_b32 v[98:99], v16 offset0:198 offset1:231
	ds_read2_b32 v[100:101], v16 offset0:8 offset1:41
	ds_read2_b32 v[102:103], v16 offset0:74 offset1:107
	ds_read2_b32 v[104:105], v16 offset0:140 offset1:173
	ds_read2_b32 v[106:107], v16 offset0:206 offset1:239
	ds_read2_b32 v[108:109], v16 offset0:16 offset1:49
	ds_read2_b32 v[110:111], v16 offset0:82 offset1:115
	ds_read2_b32 v[112:113], v16 offset0:148 offset1:181
	ds_read2_b32 v[114:115], v16 offset0:214 offset1:247
	ds_read2_b32 v[116:117], v16 offset0:24 offset1:57
	ds_read2_b32 v[118:119], v16 offset0:90 offset1:123
	ds_read2_b32 v[120:121], v16 offset0:156 offset1:189
	ds_read2_b32 v[122:123], v16 offset0:222 offset1:255
	s_waitcnt lgkmcnt(0)
	s_nop 0
	v_cvt_pk_bf16_f32 v124, v92, v93
	s_nop 0
	v_cvt_pk_bf16_f32 v125, v94, v95
	s_nop 0
	v_cvt_pk_bf16_f32 v126, v96, v97
	s_nop 0
	v_cvt_pk_bf16_f32 v127, v98, v99
	global_store_dwordx4 v[64:65], v[124:127], off
	v_add_u32_e32 v130, 24, v58
	v_ashrrev_i32_e32 v131, 31, v130
	s_nop 0
	v_cvt_pk_bf16_f32 v124, v100, v101
	s_nop 0
	v_cvt_pk_bf16_f32 v125, v102, v103
	s_nop 0
	v_cvt_pk_bf16_f32 v126, v104, v105
	s_nop 0
	v_cvt_pk_bf16_f32 v127, v106, v107
	global_store_dwordx4 v[60:61], v[124:127], off
	v_lshlrev_b64 v[130:131], 14, v[130:131]
	v_lshl_add_u64 v[130:131], v[56:57], 0, v[130:131]
	s_nop 0
	v_cvt_pk_bf16_f32 v124, v108, v109
	s_nop 0
	v_cvt_pk_bf16_f32 v125, v110, v111
	s_nop 0
	v_cvt_pk_bf16_f32 v126, v112, v113
	s_nop 0
	v_cvt_pk_bf16_f32 v127, v114, v115
	global_store_dwordx4 v[62:63], v[124:127], off
	s_nop 0
	s_nop 0
	v_cvt_pk_bf16_f32 v124, v116, v117
	s_nop 0
	v_cvt_pk_bf16_f32 v125, v118, v119
	s_nop 0
	v_cvt_pk_bf16_f32 v126, v120, v121
	s_nop 0
	v_cvt_pk_bf16_f32 v127, v122, v123
	global_store_dwordx4 v[130:131], v[124:127], off
	s_waitcnt lgkmcnt(0)
	s_cmpk_gt_i32 s8, 0x1fff
	s_cbranch_scc0 .Lrot33_top
